# speedup vs baseline: 1.0248x; 1.0110x over previous
; __device__ __forceinline__ void gmlp_item(PARAMS_T& p, int l, int b, int pos0, int tokrow0) {
;     ...
;   __syncthreads();
;   {
;     const int dim = tid >> 1, half = tid & 1;
;     const float gd = p.gm_v_g[l * 256 + dim];
;     const unsigned short* src = (const unsigned short*)(p.ws + OFF_VT) + ((size_t)b * 256 + dim) * PTOK + pos0 + half * 64;
; #pragma unroll
;     for (int i = 0; i < 8; ++i) {
;       u32x4 w = *reinterpret_cast<const u32x4*>(src + i * 8);
;       const int t0 = half * 64 + i * 8;
;       float f0 = __uint_as_float(w[0] << 16) * rs[t0 + 0] * gd, f1 = __uint_as_float(w[0] & 0xffff0000u) * rs[t0 + 1] * gd;
;       float f2 = __uint_as_float(w[1] << 16) * rs[t0 + 2] * gd, f3 = __uint_as_float(w[1] & 0xffff0000u) * rs[t0 + 3] * gd;
;       float f4 = __uint_as_float(w[2] << 16) * rs[t0 + 4] * gd, f5 = __uint_as_float(w[2] & 0xffff0000u) * rs[t0 + 5] * gd;
;       float f6 = __uint_as_float(w[3] << 16) * rs[t0 + 6] * gd, f7 = __uint_as_float(w[3] & 0xffff0000u) * rs[t0 + 7] * gd;
;       u32x4 o = {cvtpk(f0, f1), cvtpk(f2, f3), cvtpk(f4, f5), cvtpk(f6, f7)};
;       *reinterpret_cast<u32x4*>(Vn + dim * 136 + t0) = o;
;     }
;   }
.LBB0_825:
	s_or_b64 exec, exec, s[6:7]
	s_or_b32 s6, s9, 0x2000
	s_and_b64 s[4:5], s[4:5], exec
	v_ashrrev_i32_e32 v34, 1, v20
	s_cselect_b32 s6, s9, s6
	v_ashrrev_i32_e32 v35, 31, v34
	s_lshl_b64 s[4:5], s[88:89], 8
	v_lshl_add_u64 v[18:19], s[4:5], 0, v[34:35]
	v_readlane_b32 s4, v255, 34
	v_readlane_b32 s5, v255, 35
	s_movk_i32 s7, 0x4200
	v_lshlrev_b32_e32 v16, 6, v20
	v_mov_b64_e32 v[22:23], s[4:5]
	v_mad_u64_u32 v[22:23], s[4:5], v18, s7, v[22:23]
	v_mad_i32_i24 v23, v19, s7, v23
	s_lshl_b32 s88, s6, 1
	v_and_b32_e32 v21, 64, v16
	v_lshl_add_u64 v[18:19], v[22:23], 0, s[88:89]
	v_lshlrev_b32_e32 v16, 1, v21
	v_lshl_add_u64 v[18:19], v[18:19], 0, v[16:17]
	s_waitcnt lgkmcnt(0)
	s_barrier
	global_load_dwordx4 v[22:25], v[18:19], off
	s_load_dwordx2 s[6:7], s[86:87], 0x58
	s_load_dwordx2 s[4:5], s[86:87], 0x68
	v_lshl_add_u32 v36, v21, 2, 0
	v_ashrrev_i32_e32 v70, 7, v20
	v_ashrrev_i32_e32 v71, 31, v70
	s_waitcnt lgkmcnt(0)
	v_lshl_add_u64 v[26:27], v[34:35], 2, s[6:7]
	global_load_dword v35, v[26:27], off
	ds_read_b128 v[26:29], v36
	ds_read_b128 v[30:33], v36 offset:16
	s_movk_i32 s6, 0x110
	v_readlane_b32 s10, v255, 36
	v_bfe_u32 v73, v20, 5, 1
	v_bfe_u32 v76, v20, 6, 1
	v_readlane_b32 s11, v255, 37
	v_mov_b32_e32 v79, v17
	s_waitcnt vmcnt(1)
	v_lshlrev_b32_e32 v21, 16, v22
	v_and_b32_e32 v22, 0xffff0000, v22
	v_lshlrev_b32_e32 v37, 16, v23
	v_and_b32_e32 v23, 0xffff0000, v23
	v_lshlrev_b32_e32 v38, 16, v24
	v_and_b32_e32 v24, 0xffff0000, v24
	v_lshlrev_b32_e32 v39, 16, v25
	v_and_b32_e32 v25, 0xffff0000, v25
	s_waitcnt lgkmcnt(1)
	v_mul_f32_e32 v21, v26, v21
	v_mul_f32_e32 v22, v27, v22
	v_mul_f32_e32 v26, v28, v37
	v_mul_f32_e32 v23, v29, v23
	s_waitcnt lgkmcnt(0)
	v_mul_f32_e32 v27, v30, v38
	v_mul_f32_e32 v24, v31, v24
	v_mul_f32_e32 v28, v32, v39
	v_mul_f32_e32 v25, v33, v25
	s_waitcnt vmcnt(0)
	v_mul_f32_e32 v22, v35, v22
	v_mul_f32_e32 v26, v35, v26
	v_mul_f32_e32 v23, v35, v23
	v_mul_f32_e32 v27, v35, v27
	v_mul_f32_e32 v24, v35, v24
	v_mul_f32_e32 v28, v35, v28
	v_mul_f32_e32 v25, v35, v25
	v_mul_f32_e32 v21, v35, v21
	v_cvt_pk_bf16_f32 v22, v21, v22
	v_cvt_pk_bf16_f32 v23, v26, v23
	v_cvt_pk_bf16_f32 v24, v27, v24
	v_cvt_pk_bf16_f32 v25, v28, v25
	global_load_dwordx4 v[26:29], v[18:19], off offset:16
	v_mul_lo_u32 v21, v34, s6
	v_add3_u32 v34, 0, v21, v16
	ds_write_b128 v34, v[22:25] offset:1024
	ds_read_b128 v[22:25], v36 offset:32
	ds_read_b128 v[30:33], v36 offset:48
	s_waitcnt vmcnt(0)
	v_lshlrev_b32_e32 v16, 16, v26
	v_and_b32_e32 v21, 0xffff0000, v26
	v_lshlrev_b32_e32 v26, 16, v27
	v_and_b32_e32 v27, 0xffff0000, v27
	v_lshlrev_b32_e32 v37, 16, v28
	v_and_b32_e32 v28, 0xffff0000, v28
	v_lshlrev_b32_e32 v38, 16, v29
	v_and_b32_e32 v29, 0xffff0000, v29
	s_waitcnt lgkmcnt(1)
	v_mul_f32_e32 v16, v22, v16
	v_mul_f32_e32 v21, v23, v21
	v_mul_f32_e32 v22, v24, v26
	v_mul_f32_e32 v23, v25, v27
	s_waitcnt lgkmcnt(0)
	v_mul_f32_e32 v24, v30, v37
	v_mul_f32_e32 v25, v31, v28
	v_mul_f32_e32 v26, v32, v38
	v_mul_f32_e32 v27, v33, v29
	v_mul_f32_e32 v28, v35, v22
	v_mul_f32_e32 v23, v35, v23
	v_mul_f32_e32 v24, v35, v24
	v_mul_f32_e32 v25, v35, v25
	v_mul_f32_e32 v26, v35, v26
	v_mul_f32_e32 v27, v35, v27
	v_mul_f32_e32 v16, v35, v16
	v_mul_f32_e32 v21, v35, v21
	v_cvt_pk_bf16_f32 v22, v16, v21
	v_cvt_pk_bf16_f32 v23, v28, v23
	v_cvt_pk_bf16_f32 v24, v24, v25
	v_cvt_pk_bf16_f32 v25, v26, v27
	global_load_dwordx4 v[26:29], v[18:19], off offset:32
	ds_write_b128 v34, v[22:25] offset:1040
	ds_read_b128 v[22:25], v36 offset:64
	ds_read_b128 v[30:33], v36 offset:80
	s_waitcnt vmcnt(0)
	v_lshlrev_b32_e32 v16, 16, v26
	v_and_b32_e32 v21, 0xffff0000, v26
	v_lshlrev_b32_e32 v26, 16, v27
	v_and_b32_e32 v27, 0xffff0000, v27
	v_lshlrev_b32_e32 v37, 16, v28
	v_and_b32_e32 v28, 0xffff0000, v28
	v_lshlrev_b32_e32 v38, 16, v29
	v_and_b32_e32 v29, 0xffff0000, v29
	s_waitcnt lgkmcnt(1)
	v_mul_f32_e32 v16, v22, v16
	v_mul_f32_e32 v21, v23, v21
	v_mul_f32_e32 v22, v24, v26
	v_mul_f32_e32 v23, v25, v27
	s_waitcnt lgkmcnt(0)
	v_mul_f32_e32 v24, v30, v37
	v_mul_f32_e32 v25, v31, v28
	v_mul_f32_e32 v26, v32, v38
	v_mul_f32_e32 v27, v33, v29
	v_mul_f32_e32 v28, v35, v22
	v_mul_f32_e32 v23, v35, v23
	v_mul_f32_e32 v24, v35, v24
	v_mul_f32_e32 v25, v35, v25
	v_mul_f32_e32 v26, v35, v26
	v_mul_f32_e32 v27, v35, v27
	v_mul_f32_e32 v16, v35, v16
	v_mul_f32_e32 v21, v35, v21
	v_cvt_pk_bf16_f32 v22, v16, v21
	v_cvt_pk_bf16_f32 v23, v28, v23
	v_cvt_pk_bf16_f32 v24, v24, v25
	v_cvt_pk_bf16_f32 v25, v26, v27
	global_load_dwordx4 v[26:29], v[18:19], off offset:48
	ds_write_b128 v34, v[22:25] offset:1056
	ds_read_b128 v[22:25], v36 offset:96
	ds_read_b128 v[30:33], v36 offset:112
	s_waitcnt vmcnt(0)
	v_lshlrev_b32_e32 v16, 16, v26
	v_and_b32_e32 v21, 0xffff0000, v26
	v_lshlrev_b32_e32 v26, 16, v27
	v_and_b32_e32 v27, 0xffff0000, v27
	v_lshlrev_b32_e32 v37, 16, v28
	v_and_b32_e32 v28, 0xffff0000, v28
	v_lshlrev_b32_e32 v38, 16, v29
	v_and_b32_e32 v29, 0xffff0000, v29
	s_waitcnt lgkmcnt(1)
	v_mul_f32_e32 v16, v22, v16
	v_mul_f32_e32 v21, v23, v21
	v_mul_f32_e32 v22, v24, v26
	v_mul_f32_e32 v23, v25, v27
	s_waitcnt lgkmcnt(0)
	v_mul_f32_e32 v24, v30, v37
	v_mul_f32_e32 v25, v31, v28
	v_mul_f32_e32 v26, v32, v38
	v_mul_f32_e32 v27, v33, v29
	v_mul_f32_e32 v28, v35, v22
	v_mul_f32_e32 v23, v35, v23
	v_mul_f32_e32 v24, v35, v24
	v_mul_f32_e32 v25, v35, v25
	v_mul_f32_e32 v26, v35, v26
	v_mul_f32_e32 v27, v35, v27
	v_mul_f32_e32 v16, v35, v16
	v_mul_f32_e32 v21, v35, v21
	v_cvt_pk_bf16_f32 v22, v16, v21
	v_cvt_pk_bf16_f32 v23, v28, v23
	v_cvt_pk_bf16_f32 v24, v24, v25
	v_cvt_pk_bf16_f32 v25, v26, v27
	global_load_dwordx4 v[26:29], v[18:19], off offset:64
	ds_write_b128 v34, v[22:25] offset:1072
	ds_read_b128 v[22:25], v36 offset:128
	ds_read_b128 v[30:33], v36 offset:144
	s_waitcnt vmcnt(0)
; __device__ __forceinline__ void gmlp_item(PARAMS_T& p, int l, int b, int pos0, int tokrow0) {
;     ...
; #pragma unroll
;     for (int i = 0; i < 8; ++i) {
;       u32x4 w = *reinterpret_cast<const u32x4*>(src + i * 8);
;       const int t0 = half * 64 + i * 8;
;       float f0 = __uint_as_float(w[0] << 16) * rs[t0 + 0] * gd, f1 = __uint_as_float(w[0] & 0xffff0000u) * rs[t0 + 1] * gd;
;       float f2 = __uint_as_float(w[1] << 16) * rs[t0 + 2] * gd, f3 = __uint_as_float(w[1] & 0xffff0000u) * rs[t0 + 3] * gd;
;       float f4 = __uint_as_float(w[2] << 16) * rs[t0 + 4] * gd, f5 = __uint_as_float(w[2] & 0xffff0000u) * rs[t0 + 5] * gd;
;       float f6 = __uint_as_float(w[3] << 16) * rs[t0 + 6] * gd, f7 = __uint_as_float(w[3] & 0xffff0000u) * rs[t0 + 7] * gd;
;       u32x4 o = {cvtpk(f0, f1), cvtpk(f2, f3), cvtpk(f4, f5), cvtpk(f6, f7)};
;       *reinterpret_cast<u32x4*>(Vn + dim * 136 + t0) = o;
;     }
;   }
;   __syncthreads();
	v_lshlrev_b32_e32 v16, 16, v26
	v_and_b32_e32 v21, 0xffff0000, v26
	v_lshlrev_b32_e32 v26, 16, v27
	v_and_b32_e32 v27, 0xffff0000, v27
	v_lshlrev_b32_e32 v37, 16, v28
	v_and_b32_e32 v28, 0xffff0000, v28
	v_lshlrev_b32_e32 v38, 16, v29
	v_and_b32_e32 v29, 0xffff0000, v29
	s_waitcnt lgkmcnt(1)
	v_mul_f32_e32 v16, v22, v16
	v_mul_f32_e32 v21, v23, v21
	v_mul_f32_e32 v22, v24, v26
	v_mul_f32_e32 v23, v25, v27
	s_waitcnt lgkmcnt(0)
	v_mul_f32_e32 v24, v30, v37
	v_mul_f32_e32 v25, v31, v28
	v_mul_f32_e32 v26, v32, v38
	v_mul_f32_e32 v27, v33, v29
	v_mul_f32_e32 v28, v35, v22
	v_mul_f32_e32 v23, v35, v23
	v_mul_f32_e32 v24, v35, v24
	v_mul_f32_e32 v25, v35, v25
	v_mul_f32_e32 v26, v35, v26
	v_mul_f32_e32 v27, v35, v27
	v_mul_f32_e32 v16, v35, v16
	v_mul_f32_e32 v21, v35, v21
	v_cvt_pk_bf16_f32 v22, v16, v21
	v_cvt_pk_bf16_f32 v23, v28, v23
	v_cvt_pk_bf16_f32 v24, v24, v25
	v_cvt_pk_bf16_f32 v25, v26, v27
	global_load_dwordx4 v[26:29], v[18:19], off offset:80
	ds_write_b128 v34, v[22:25] offset:1088
	ds_read_b128 v[22:25], v36 offset:160
	ds_read_b128 v[30:33], v36 offset:176
	s_waitcnt vmcnt(0)
	v_lshlrev_b32_e32 v16, 16, v26
	v_and_b32_e32 v21, 0xffff0000, v26
	v_lshlrev_b32_e32 v26, 16, v27
	v_and_b32_e32 v27, 0xffff0000, v27
	v_lshlrev_b32_e32 v37, 16, v28
	v_and_b32_e32 v28, 0xffff0000, v28
	v_lshlrev_b32_e32 v38, 16, v29
	v_and_b32_e32 v29, 0xffff0000, v29
	s_waitcnt lgkmcnt(1)
	v_mul_f32_e32 v16, v22, v16
	v_mul_f32_e32 v21, v23, v21
	v_mul_f32_e32 v22, v24, v26
	v_mul_f32_e32 v23, v25, v27
	s_waitcnt lgkmcnt(0)
	v_mul_f32_e32 v24, v30, v37
	v_mul_f32_e32 v25, v31, v28
	v_mul_f32_e32 v26, v32, v38
	v_mul_f32_e32 v27, v33, v29
	v_mul_f32_e32 v28, v35, v22
	v_mul_f32_e32 v23, v35, v23
	v_mul_f32_e32 v24, v35, v24
	v_mul_f32_e32 v25, v35, v25
	v_mul_f32_e32 v26, v35, v26
	v_mul_f32_e32 v27, v35, v27
	v_mul_f32_e32 v16, v35, v16
	v_mul_f32_e32 v21, v35, v21
	v_cvt_pk_bf16_f32 v22, v16, v21
	v_cvt_pk_bf16_f32 v23, v28, v23
	v_cvt_pk_bf16_f32 v24, v24, v25
	v_cvt_pk_bf16_f32 v25, v26, v27
	global_load_dwordx4 v[26:29], v[18:19], off offset:96
	ds_write_b128 v34, v[22:25] offset:1104
	ds_read_b128 v[22:25], v36 offset:192
	ds_read_b128 v[30:33], v36 offset:208
	s_waitcnt vmcnt(0)
	v_lshlrev_b32_e32 v16, 16, v26
	v_and_b32_e32 v21, 0xffff0000, v26
	v_lshlrev_b32_e32 v26, 16, v27
	v_and_b32_e32 v27, 0xffff0000, v27
	v_lshlrev_b32_e32 v37, 16, v28
	v_and_b32_e32 v28, 0xffff0000, v28
	v_lshlrev_b32_e32 v38, 16, v29
	v_and_b32_e32 v29, 0xffff0000, v29
	s_waitcnt lgkmcnt(1)
	v_mul_f32_e32 v16, v22, v16
	v_mul_f32_e32 v21, v23, v21
	v_mul_f32_e32 v22, v24, v26
	v_mul_f32_e32 v23, v25, v27
	s_waitcnt lgkmcnt(0)
	v_mul_f32_e32 v24, v30, v37
	v_mul_f32_e32 v25, v31, v28
	v_mul_f32_e32 v26, v32, v38
	v_mul_f32_e32 v27, v33, v29
	v_mul_f32_e32 v28, v35, v22
	v_mul_f32_e32 v23, v35, v23
	v_mul_f32_e32 v24, v35, v24
	v_mul_f32_e32 v25, v35, v25
	v_mul_f32_e32 v26, v35, v26
	v_mul_f32_e32 v27, v35, v27
	v_mul_f32_e32 v16, v35, v16
	v_mul_f32_e32 v21, v35, v21
	v_cvt_pk_bf16_f32 v22, v16, v21
	v_cvt_pk_bf16_f32 v23, v28, v23
	v_cvt_pk_bf16_f32 v24, v24, v25
	v_cvt_pk_bf16_f32 v25, v26, v27
	global_load_dwordx4 v[26:29], v[18:19], off offset:112
	v_and_b32_e32 v30, 31, v20
	v_lshlrev_b32_e32 v16, 8, v30
	v_lshlrev_b64 v[18:19], 15, v[70:71]
	v_lshl_or_b32 v78, v76, 14, v16
	v_lshl_add_u64 v[18:19], s[10:11], 0, v[18:19]
	v_lshlrev_b32_e32 v16, 4, v73
	ds_write_b128 v34, v[22:25] offset:1120
	v_lshl_add_u64 v[80:81], v[18:19], 0, v[16:17]
	ds_read_b128 v[18:21], v36 offset:224
	ds_read_b128 v[22:25], v36 offset:240
	v_lshl_add_u64 v[74:75], v[80:81], 0, v[78:79]
	v_lshl_or_b32 v72, v70, 6, v30
	v_lshlrev_b64 v[70:71], 9, v[70:71]
	s_waitcnt vmcnt(0)
	v_lshlrev_b32_e32 v31, 16, v26
	v_and_b32_e32 v26, 0xffff0000, v26
	v_lshlrev_b32_e32 v32, 16, v27
	v_and_b32_e32 v27, 0xffff0000, v27
	v_lshlrev_b32_e32 v33, 16, v28
	v_and_b32_e32 v28, 0xffff0000, v28
	v_lshlrev_b32_e32 v36, 16, v29
	v_and_b32_e32 v29, 0xffff0000, v29
	s_waitcnt lgkmcnt(1)
	v_mul_f32_e32 v18, v18, v31
	v_mul_f32_e32 v19, v19, v26
	v_mul_f32_e32 v20, v20, v32
	v_mul_f32_e32 v21, v21, v27
	s_waitcnt lgkmcnt(0)
	v_mul_f32_e32 v22, v22, v33
	v_mul_f32_e32 v23, v23, v28
	v_mul_f32_e32 v24, v24, v36
	v_mul_f32_e32 v25, v25, v29
	v_mul_f32_e32 v18, v35, v18
	v_mul_f32_e32 v19, v35, v19
	v_mul_f32_e32 v20, v35, v20
	v_mul_f32_e32 v21, v35, v21
	v_mul_f32_e32 v22, v35, v22
	v_mul_f32_e32 v23, v35, v23
	v_mul_f32_e32 v24, v35, v24
	v_mul_f32_e32 v25, v35, v25
	v_cvt_pk_bf16_f32 v18, v18, v19
	v_cvt_pk_bf16_f32 v19, v20, v21
	v_cvt_pk_bf16_f32 v20, v22, v23
	v_cvt_pk_bf16_f32 v21, v24, v25
	ds_write_b128 v34, v[18:21] offset:1136
	s_waitcnt lgkmcnt(0)
	s_barrier
; __device__ __forceinline__ int crow(int r, int hi) { return (r & 3) + 8 * (r >> 2) + 4 * hi; }
; __device__ __forceinline__ void gmlp_item(PARAMS_T& p, int l, int b, int pos0, int tokrow0) {
;     ...
;   const int g = wid >> 1, th = wid & 1;
;   const bf16* wsb = (const bf16*)(p.ws + OFF_WSBF) + ((size_t)l * 4 + g) * 128 * 128;
;   f32x16 acc[2][2] = {};
; #pragma unroll
;   for (int ks = 0; ks < 8; ++ks) {
;     bf16x8 af[2], bfr[2];
; #pragma unroll
;     for (int tb = 0; tb < 2; ++tb) af[tb] = *reinterpret_cast<const bf16x8*>(wsb + (size_t)(th * 64 + tb * 32 + r32) * 128 + ks * 16 + hi * 8);
; #pragma unroll
;     for (int db = 0; db < 2; ++db) bfr[db] = *reinterpret_cast<const bf16x8*>(Vn + (g * 64 + db * 32 + r32) * 136 + ks * 16 + hi * 8);
; #pragma unroll
;     for (int tb = 0; tb < 2; ++tb)
; #pragma unroll
;       for (int db = 0; db < 2; ++db) acc[tb][db] = __builtin_amdgcn_mfma_f32_32x32x16_bf16(af[tb], bfr[db], acc[tb][db], 0, 0, 0);
;     ...
;   const float* bs = p.gm_bs + ((size_t)l * 4 + g) * 128;
;   const unsigned short* u = (const unsigned short*)(p.ws + OFF_U);
;   unsigned short* outp = (unsigned short*)(p.ws + OFF_ACTA);
; #pragma unroll
;   for (int tb = 0; tb < 2; ++tb)
; #pragma unroll
;     for (int r = 0; r < 16; ++r) {
;       const int t = th * 64 + tb * 32 + crow(r, hi);
;       const float bt = bs[t];
; #pragma unroll
;       for (int db = 0; db < 2; ++db) {
;         const int d = g * 64 + db * 32 + r32;
;         const float uv = __uint_as_float(((unsigned)u[(size_t)(tokrow0 + t) * 256 + d]) << 16);
	v_and_b32_e32 v250, 31, v192
	v_bfe_u32 v251, v192, 5, 1
	v_lshrrev_b32_e32 v252, 7, v192
	v_bfe_u32 v253, v192, 6, 1
	v_lshl_or_b32 v254, v252, 6, v250
	v_lshlrev_b32_e32 v172, 1, v254
	v_mul_u32_u24_e32 v254, 0x110, v254
	v_lshl_add_u32 v254, v251, 4, v254
	v_add_u32_e32 v16, 0x400, v254
	v_lshl_or_b32 v254, v253, 6, v250
	v_lshlrev_b32_e32 v254, 8, v254
	v_lshl_or_b32 v254, v251, 4, v254
	v_lshl_add_u32 v254, v252, 15, v254
	v_mov_b32_e32 v162, v254
	v_mov_b32_e32 v163, 0
	v_lshl_add_u64 v[162:163], s[10:11], 0, v[162:163]
	v_mov_b32_e32 v164, 0x2000
	v_mov_b32_e32 v165, 0
	v_lshl_add_u64 v[164:165], v[162:163], 0, v[164:165]
	global_load_dwordx4 v[82:85], v[162:163], off
	global_load_dwordx4 v[86:89], v[164:165], off
	global_load_dwordx4 v[90:93], v[162:163], off offset:32
	global_load_dwordx4 v[94:97], v[164:165], off offset:32
	global_load_dwordx4 v[98:101], v[162:163], off offset:64
	global_load_dwordx4 v[102:105], v[164:165], off offset:64
	global_load_dwordx4 v[106:109], v[162:163], off offset:96
	global_load_dwordx4 v[110:113], v[164:165], off offset:96
	global_load_dwordx4 v[114:117], v[162:163], off offset:128
	global_load_dwordx4 v[118:121], v[164:165], off offset:128
	global_load_dwordx4 v[122:125], v[162:163], off offset:160
	global_load_dwordx4 v[126:129], v[164:165], off offset:160
	global_load_dwordx4 v[130:133], v[162:163], off offset:192
	global_load_dwordx4 v[134:137], v[164:165], off offset:192
	global_load_dwordx4 v[138:141], v[162:163], off offset:224
	global_load_dwordx4 v[142:145], v[164:165], off offset:224
	v_lshlrev_b32_e32 v171, 6, v253
	v_lshl_add_u32 v171, v251, 2, v171
	v_lshl_add_u32 v170, v252, 7, v171
	v_lshlrev_b32_e32 v170, 2, v170
	v_add_u32_e32 v171, s8, v171
	v_add_u32_e32 v254, 0, v171
	v_lshl_add_u32 v162, v254, 9, v172
	v_add_u32_e32 v254, 8, v171
	v_lshl_add_u32 v163, v254, 9, v172
	v_add_u32_e32 v254, 16, v171
	v_lshl_add_u32 v164, v254, 9, v172
	v_add_u32_e32 v254, 24, v171
	v_lshl_add_u32 v165, v254, 9, v172
	v_add_u32_e32 v254, 32, v171
	v_lshl_add_u32 v166, v254, 9, v172
	v_add_u32_e32 v254, 40, v171
	v_lshl_add_u32 v167, v254, 9, v172
	v_add_u32_e32 v254, 48, v171
	v_lshl_add_u32 v168, v254, 9, v172
	v_add_u32_e32 v254, 56, v171
	v_lshl_add_u32 v169, v254, 9, v172
	v_mov_b32_e32 v18, 0
	v_mov_b32_e32 v19, 0
	v_mov_b32_e32 v20, 0
	v_mov_b32_e32 v21, 0
	v_mov_b32_e32 v22, 0
	v_mov_b32_e32 v23, 0
	v_mov_b32_e32 v24, 0
	v_mov_b32_e32 v25, 0
	v_mov_b32_e32 v26, 0
	v_mov_b32_e32 v27, 0
	v_mov_b32_e32 v28, 0
	v_mov_b32_e32 v29, 0
	v_mov_b32_e32 v30, 0
	v_mov_b32_e32 v31, 0
	v_mov_b32_e32 v32, 0
	v_mov_b32_e32 v33, 0
	v_mov_b32_e32 v34, 0
	v_mov_b32_e32 v35, 0
	v_mov_b32_e32 v36, 0
	v_mov_b32_e32 v37, 0
	v_mov_b32_e32 v38, 0
	v_mov_b32_e32 v39, 0
	v_mov_b32_e32 v40, 0
	v_mov_b32_e32 v41, 0
	v_mov_b32_e32 v42, 0
	v_mov_b32_e32 v43, 0
	v_mov_b32_e32 v44, 0
	v_mov_b32_e32 v45, 0
	v_mov_b32_e32 v46, 0
	v_mov_b32_e32 v47, 0
	v_mov_b32_e32 v48, 0
	v_mov_b32_e32 v49, 0
	v_mov_b32_e32 v50, 0
	v_mov_b32_e32 v51, 0
	v_mov_b32_e32 v52, 0
	v_mov_b32_e32 v53, 0
	v_mov_b32_e32 v54, 0
	v_mov_b32_e32 v55, 0
	v_mov_b32_e32 v56, 0
	v_mov_b32_e32 v57, 0
	v_mov_b32_e32 v58, 0
	v_mov_b32_e32 v59, 0
	v_mov_b32_e32 v60, 0
	v_mov_b32_e32 v61, 0
	v_mov_b32_e32 v62, 0
	v_mov_b32_e32 v63, 0
	v_mov_b32_e32 v64, 0
	v_mov_b32_e32 v65, 0
	v_mov_b32_e32 v66, 0
	v_mov_b32_e32 v67, 0
	v_mov_b32_e32 v68, 0
	v_mov_b32_e32 v69, 0
	v_mov_b32_e32 v70, 0
	v_mov_b32_e32 v71, 0
	v_mov_b32_e32 v72, 0
	v_mov_b32_e32 v73, 0
	v_mov_b32_e32 v74, 0
	v_mov_b32_e32 v75, 0
	v_mov_b32_e32 v76, 0
	v_mov_b32_e32 v77, 0
	v_mov_b32_e32 v78, 0
	v_mov_b32_e32 v79, 0
	v_mov_b32_e32 v80, 0
	v_mov_b32_e32 v81, 0
	ds_read_b128 v[146:149], v16 offset:0
	ds_read_b128 v[150:153], v16 offset:8704
	ds_read_b128 v[154:157], v16 offset:32
	ds_read_b128 v[158:161], v16 offset:8736
	ds_read_b128 v[234:237], v16 offset:64
	ds_read_b128 v[238:241], v16 offset:8768
	ds_read_b128 v[242:245], v16 offset:96
	ds_read_b128 v[246:249], v16 offset:8800
	s_waitcnt vmcnt(15) lgkmcnt(7)
	v_mfma_f32_32x32x16_bf16 v[18:33], v[82:85], v[146:149], v[18:33]
	s_waitcnt vmcnt(15) lgkmcnt(6)
	v_mfma_f32_32x32x16_bf16 v[34:49], v[82:85], v[150:153], v[34:49]
	s_waitcnt vmcnt(14)
	v_mfma_f32_32x32x16_bf16 v[50:65], v[86:89], v[146:149], v[50:65]
	v_mfma_f32_32x32x16_bf16 v[66:81], v[86:89], v[150:153], v[66:81]
	s_waitcnt vmcnt(13) lgkmcnt(5)
	v_mfma_f32_32x32x16_bf16 v[18:33], v[90:93], v[154:157], v[18:33]
	s_waitcnt vmcnt(13) lgkmcnt(4)
	v_mfma_f32_32x32x16_bf16 v[34:49], v[90:93], v[158:161], v[34:49]
	s_waitcnt vmcnt(12)
	v_mfma_f32_32x32x16_bf16 v[50:65], v[94:97], v[154:157], v[50:65]
	v_mfma_f32_32x32x16_bf16 v[66:81], v[94:97], v[158:161], v[66:81]
	s_waitcnt vmcnt(11) lgkmcnt(3)
	v_mfma_f32_32x32x16_bf16 v[18:33], v[98:101], v[234:237], v[18:33]
	s_waitcnt vmcnt(11) lgkmcnt(2)
	v_mfma_f32_32x32x16_bf16 v[34:49], v[98:101], v[238:241], v[34:49]
	s_waitcnt vmcnt(10)
	v_mfma_f32_32x32x16_bf16 v[50:65], v[102:105], v[234:237], v[50:65]
	v_mfma_f32_32x32x16_bf16 v[66:81], v[102:105], v[238:241], v[66:81]
	s_waitcnt vmcnt(9) lgkmcnt(1)
	v_mfma_f32_32x32x16_bf16 v[18:33], v[106:109], v[242:245], v[18:33]
	s_waitcnt vmcnt(9) lgkmcnt(0)
	v_mfma_f32_32x32x16_bf16 v[34:49], v[106:109], v[246:249], v[34:49]
	s_waitcnt vmcnt(8)
	v_mfma_f32_32x32x16_bf16 v[50:65], v[110:113], v[242:245], v[50:65]
	v_mfma_f32_32x32x16_bf16 v[66:81], v[110:113], v[246:249], v[66:81]
	ds_read_b128 v[146:149], v16 offset:128
	ds_read_b128 v[150:153], v16 offset:8832
	ds_read_b128 v[154:157], v16 offset:160
	ds_read_b128 v[158:161], v16 offset:8864
	ds_read_b128 v[234:237], v16 offset:192
	ds_read_b128 v[238:241], v16 offset:8896
	ds_read_b128 v[242:245], v16 offset:224
	ds_read_b128 v[246:249], v16 offset:8928
	s_waitcnt vmcnt(7) lgkmcnt(7)
; __device__ __forceinline__ unsigned short bf1(float a) { return (unsigned short)(cvtpk(a, 0.f) & 0xffffu); }
; __device__ __forceinline__ int crow(int r, int hi) { return (r & 3) + 8 * (r >> 2) + 4 * hi; }
; __device__ __forceinline__ void gmlp_item(PARAMS_T& p, int l, int b, int pos0, int tokrow0) {
;     ...
; #pragma unroll
;   for (int ks = 0; ks < 8; ++ks) {
;     bf16x8 af[2], bfr[2];
; #pragma unroll
;     for (int tb = 0; tb < 2; ++tb) af[tb] = *reinterpret_cast<const bf16x8*>(wsb + (size_t)(th * 64 + tb * 32 + r32) * 128 + ks * 16 + hi * 8);
; #pragma unroll
;     for (int db = 0; db < 2; ++db) bfr[db] = *reinterpret_cast<const bf16x8*>(Vn + (g * 64 + db * 32 + r32) * 136 + ks * 16 + hi * 8);
; #pragma unroll
;     for (int tb = 0; tb < 2; ++tb)
; #pragma unroll
;       for (int db = 0; db < 2; ++db) acc[tb][db] = __builtin_amdgcn_mfma_f32_32x32x16_bf16(af[tb], bfr[db], acc[tb][db], 0, 0, 0);
;   }
;     ...
;   for (int tb = 0; tb < 2; ++tb)
; #pragma unroll
;     for (int r = 0; r < 16; ++r) {
;       const int t = th * 64 + tb * 32 + crow(r, hi);
;       const float bt = bs[t];
; #pragma unroll
;       for (int db = 0; db < 2; ++db) {
;         const int d = g * 64 + db * 32 + r32;
;         const float uv = __uint_as_float(((unsigned)u[(size_t)(tokrow0 + t) * 256 + d]) << 16);
;         outp[(size_t)(tokrow0 + t) * 1024 + 256 + d] = bf1(uv * (acc[tb][db][r] + bt));
	v_mfma_f32_32x32x16_bf16 v[18:33], v[114:117], v[146:149], v[18:33]
	s_waitcnt vmcnt(7) lgkmcnt(6)
	v_mfma_f32_32x32x16_bf16 v[34:49], v[114:117], v[150:153], v[34:49]
	s_waitcnt vmcnt(6)
	v_mfma_f32_32x32x16_bf16 v[50:65], v[118:121], v[146:149], v[50:65]
	v_mfma_f32_32x32x16_bf16 v[66:81], v[118:121], v[150:153], v[66:81]
	s_waitcnt vmcnt(5) lgkmcnt(5)
	v_mfma_f32_32x32x16_bf16 v[18:33], v[122:125], v[154:157], v[18:33]
	s_waitcnt vmcnt(5) lgkmcnt(4)
	v_mfma_f32_32x32x16_bf16 v[34:49], v[122:125], v[158:161], v[34:49]
	s_waitcnt vmcnt(4)
	v_mfma_f32_32x32x16_bf16 v[50:65], v[126:129], v[154:157], v[50:65]
	v_mfma_f32_32x32x16_bf16 v[66:81], v[126:129], v[158:161], v[66:81]
	s_waitcnt vmcnt(3) lgkmcnt(3)
	v_mfma_f32_32x32x16_bf16 v[18:33], v[130:133], v[234:237], v[18:33]
	s_waitcnt vmcnt(3) lgkmcnt(2)
	v_mfma_f32_32x32x16_bf16 v[34:49], v[130:133], v[238:241], v[34:49]
	s_waitcnt vmcnt(2)
	v_mfma_f32_32x32x16_bf16 v[50:65], v[134:137], v[234:237], v[50:65]
	v_mfma_f32_32x32x16_bf16 v[66:81], v[134:137], v[238:241], v[66:81]
	s_waitcnt vmcnt(1) lgkmcnt(1)
	v_mfma_f32_32x32x16_bf16 v[18:33], v[138:141], v[242:245], v[18:33]
	s_waitcnt vmcnt(1) lgkmcnt(0)
	v_mfma_f32_32x32x16_bf16 v[34:49], v[138:141], v[246:249], v[34:49]
	s_waitcnt vmcnt(0)
	v_mfma_f32_32x32x16_bf16 v[50:65], v[142:145], v[242:245], v[50:65]
	v_mfma_f32_32x32x16_bf16 v[66:81], v[142:145], v[246:249], v[66:81]
	global_load_ushort v82, v162, s[80:81]
	global_load_ushort v83, v162, s[80:81] offset:64
	global_load_dword v146, v170, s[4:5]
	global_load_ushort v84, v162, s[80:81] offset:512
	global_load_ushort v85, v162, s[80:81] offset:576
	global_load_dword v147, v170, s[4:5] offset:4
	global_load_ushort v86, v162, s[80:81] offset:1024
	global_load_ushort v87, v162, s[80:81] offset:1088
	global_load_dword v148, v170, s[4:5] offset:8
	global_load_ushort v88, v162, s[80:81] offset:1536
	global_load_ushort v89, v162, s[80:81] offset:1600
	global_load_dword v149, v170, s[4:5] offset:12
	global_load_ushort v90, v163, s[80:81]
	global_load_ushort v91, v163, s[80:81] offset:64
	global_load_dword v150, v170, s[4:5] offset:32
	global_load_ushort v92, v163, s[80:81] offset:512
	global_load_ushort v93, v163, s[80:81] offset:576
	global_load_dword v151, v170, s[4:5] offset:36
	global_load_ushort v94, v163, s[80:81] offset:1024
	global_load_ushort v95, v163, s[80:81] offset:1088
	global_load_dword v152, v170, s[4:5] offset:40
	global_load_ushort v96, v163, s[80:81] offset:1536
	global_load_ushort v97, v163, s[80:81] offset:1600
	global_load_dword v153, v170, s[4:5] offset:44
	global_load_ushort v98, v164, s[80:81]
	global_load_ushort v99, v164, s[80:81] offset:64
	global_load_dword v154, v170, s[4:5] offset:64
	global_load_ushort v100, v164, s[80:81] offset:512
	global_load_ushort v101, v164, s[80:81] offset:576
	global_load_dword v155, v170, s[4:5] offset:68
	global_load_ushort v102, v164, s[80:81] offset:1024
	global_load_ushort v103, v164, s[80:81] offset:1088
	global_load_dword v156, v170, s[4:5] offset:72
	global_load_ushort v104, v164, s[80:81] offset:1536
	global_load_ushort v105, v164, s[80:81] offset:1600
	global_load_dword v157, v170, s[4:5] offset:76
	global_load_ushort v106, v165, s[80:81]
	global_load_ushort v107, v165, s[80:81] offset:64
	global_load_dword v158, v170, s[4:5] offset:96
	global_load_ushort v108, v165, s[80:81] offset:512
	global_load_ushort v109, v165, s[80:81] offset:576
	global_load_dword v159, v170, s[4:5] offset:100
	global_load_ushort v110, v165, s[80:81] offset:1024
	global_load_ushort v111, v165, s[80:81] offset:1088
	global_load_dword v160, v170, s[4:5] offset:104
	global_load_ushort v112, v165, s[80:81] offset:1536
	global_load_ushort v113, v165, s[80:81] offset:1600
	global_load_dword v161, v170, s[4:5] offset:108
	global_load_ushort v114, v166, s[80:81]
	global_load_ushort v115, v166, s[80:81] offset:64
	global_load_dword v234, v170, s[4:5] offset:128
	global_load_ushort v116, v166, s[80:81] offset:512
	global_load_ushort v117, v166, s[80:81] offset:576
	global_load_dword v235, v170, s[4:5] offset:132
	global_load_ushort v118, v166, s[80:81] offset:1024
	global_load_ushort v119, v166, s[80:81] offset:1088
	global_load_dword v236, v170, s[4:5] offset:136
	global_load_ushort v120, v166, s[80:81] offset:1536
	global_load_ushort v121, v166, s[80:81] offset:1600
	global_load_dword v237, v170, s[4:5] offset:140
	global_load_ushort v122, v167, s[80:81]
	global_load_ushort v123, v167, s[80:81] offset:64
	global_load_dword v238, v170, s[4:5] offset:160
	global_load_ushort v124, v167, s[80:81] offset:512
	global_load_ushort v125, v167, s[80:81] offset:576
	global_load_dword v239, v170, s[4:5] offset:164
	global_load_ushort v126, v167, s[80:81] offset:1024
	global_load_ushort v127, v167, s[80:81] offset:1088
	global_load_dword v240, v170, s[4:5] offset:168
	global_load_ushort v128, v167, s[80:81] offset:1536
	global_load_ushort v129, v167, s[80:81] offset:1600
	global_load_dword v241, v170, s[4:5] offset:172
	global_load_ushort v130, v168, s[80:81]
	global_load_ushort v131, v168, s[80:81] offset:64
	global_load_dword v242, v170, s[4:5] offset:192
	global_load_ushort v132, v168, s[80:81] offset:512
	global_load_ushort v133, v168, s[80:81] offset:576
	global_load_dword v243, v170, s[4:5] offset:196
	global_load_ushort v134, v168, s[80:81] offset:1024
	global_load_ushort v135, v168, s[80:81] offset:1088
	global_load_dword v244, v170, s[4:5] offset:200
	global_load_ushort v136, v168, s[80:81] offset:1536
	global_load_ushort v137, v168, s[80:81] offset:1600
	global_load_dword v245, v170, s[4:5] offset:204
	global_load_ushort v138, v169, s[80:81]
	global_load_ushort v139, v169, s[80:81] offset:64
	global_load_dword v246, v170, s[4:5] offset:224
	global_load_ushort v140, v169, s[80:81] offset:512
	global_load_ushort v141, v169, s[80:81] offset:576
	global_load_dword v247, v170, s[4:5] offset:228
	global_load_ushort v142, v169, s[80:81] offset:1024
	global_load_ushort v143, v169, s[80:81] offset:1088
	global_load_dword v248, v170, s[4:5] offset:232
	global_load_ushort v144, v169, s[80:81] offset:1536
	global_load_ushort v145, v169, s[80:81] offset:1600
	global_load_dword v249, v170, s[4:5] offset:236
	s_waitcnt vmcnt(63)
; __device__ __forceinline__ unsigned short bf1(float a) { return (unsigned short)(cvtpk(a, 0.f) & 0xffffu); }
; __device__ __forceinline__ int crow(int r, int hi) { return (r & 3) + 8 * (r >> 2) + 4 * hi; }
; __device__ __forceinline__ void gmlp_item(PARAMS_T& p, int l, int b, int pos0, int tokrow0) {
;     ...
;   for (int tb = 0; tb < 2; ++tb)
; #pragma unroll
;     for (int r = 0; r < 16; ++r) {
;       const int t = th * 64 + tb * 32 + crow(r, hi);
;       const float bt = bs[t];
; #pragma unroll
;       for (int db = 0; db < 2; ++db) {
;         const int d = g * 64 + db * 32 + r32;
;         const float uv = __uint_as_float(((unsigned)u[(size_t)(tokrow0 + t) * 256 + d]) << 16);
;         outp[(size_t)(tokrow0 + t) * 1024 + 256 + d] = bf1(uv * (acc[tb][db][r] + bt));
	v_add_f32_e32 v250, v18, v146
	v_lshlrev_b32_e32 v82, 16, v82
	v_mul_f32_e32 v82, v250, v82
	v_cvt_pk_bf16_f32 v82, v82, v17
	v_add_f32_e32 v251, v34, v146
	v_lshlrev_b32_e32 v83, 16, v83
	v_mul_f32_e32 v83, v251, v83
	v_cvt_pk_bf16_f32 v83, v83, v17
	s_waitcnt vmcnt(63)
	v_add_f32_e32 v250, v19, v147
	v_lshlrev_b32_e32 v84, 16, v84
	v_mul_f32_e32 v84, v250, v84
	v_cvt_pk_bf16_f32 v84, v84, v17
	v_add_f32_e32 v251, v35, v147
	v_lshlrev_b32_e32 v85, 16, v85
	v_mul_f32_e32 v85, v251, v85
	v_cvt_pk_bf16_f32 v85, v85, v17
	s_waitcnt vmcnt(63)
	v_add_f32_e32 v250, v20, v148
	v_lshlrev_b32_e32 v86, 16, v86
	v_mul_f32_e32 v86, v250, v86
	v_cvt_pk_bf16_f32 v86, v86, v17
	v_add_f32_e32 v251, v36, v148
	v_lshlrev_b32_e32 v87, 16, v87
	v_mul_f32_e32 v87, v251, v87
	v_cvt_pk_bf16_f32 v87, v87, v17
	s_waitcnt vmcnt(63)
	v_add_f32_e32 v250, v21, v149
	v_lshlrev_b32_e32 v88, 16, v88
	v_mul_f32_e32 v88, v250, v88
	v_cvt_pk_bf16_f32 v88, v88, v17
	v_add_f32_e32 v251, v37, v149
	v_lshlrev_b32_e32 v89, 16, v89
	v_mul_f32_e32 v89, v251, v89
	v_cvt_pk_bf16_f32 v89, v89, v17
	s_waitcnt vmcnt(63)
	v_add_f32_e32 v250, v22, v150
	v_lshlrev_b32_e32 v90, 16, v90
	v_mul_f32_e32 v90, v250, v90
	v_cvt_pk_bf16_f32 v90, v90, v17
	v_add_f32_e32 v251, v38, v150
	v_lshlrev_b32_e32 v91, 16, v91
	v_mul_f32_e32 v91, v251, v91
	v_cvt_pk_bf16_f32 v91, v91, v17
	s_waitcnt vmcnt(63)
	v_add_f32_e32 v250, v23, v151
	v_lshlrev_b32_e32 v92, 16, v92
	v_mul_f32_e32 v92, v250, v92
	v_cvt_pk_bf16_f32 v92, v92, v17
	v_add_f32_e32 v251, v39, v151
	v_lshlrev_b32_e32 v93, 16, v93
	v_mul_f32_e32 v93, v251, v93
	v_cvt_pk_bf16_f32 v93, v93, v17
	s_waitcnt vmcnt(63)
	v_add_f32_e32 v250, v24, v152
	v_lshlrev_b32_e32 v94, 16, v94
	v_mul_f32_e32 v94, v250, v94
	v_cvt_pk_bf16_f32 v94, v94, v17
	v_add_f32_e32 v251, v40, v152
	v_lshlrev_b32_e32 v95, 16, v95
	v_mul_f32_e32 v95, v251, v95
	v_cvt_pk_bf16_f32 v95, v95, v17
	s_waitcnt vmcnt(63)
	v_add_f32_e32 v250, v25, v153
	v_lshlrev_b32_e32 v96, 16, v96
	v_mul_f32_e32 v96, v250, v96
	v_cvt_pk_bf16_f32 v96, v96, v17
	v_add_f32_e32 v251, v41, v153
	v_lshlrev_b32_e32 v97, 16, v97
	v_mul_f32_e32 v97, v251, v97
	v_cvt_pk_bf16_f32 v97, v97, v17
	s_waitcnt vmcnt(63)
	v_add_f32_e32 v250, v26, v154
	v_lshlrev_b32_e32 v98, 16, v98
	v_mul_f32_e32 v98, v250, v98
	v_cvt_pk_bf16_f32 v98, v98, v17
	v_add_f32_e32 v251, v42, v154
	v_lshlrev_b32_e32 v99, 16, v99
	v_mul_f32_e32 v99, v251, v99
	v_cvt_pk_bf16_f32 v99, v99, v17
	s_waitcnt vmcnt(63)
	v_add_f32_e32 v250, v27, v155
	v_lshlrev_b32_e32 v100, 16, v100
	v_mul_f32_e32 v100, v250, v100
	v_cvt_pk_bf16_f32 v100, v100, v17
	v_add_f32_e32 v251, v43, v155
	v_lshlrev_b32_e32 v101, 16, v101
	v_mul_f32_e32 v101, v251, v101
	v_cvt_pk_bf16_f32 v101, v101, v17
	s_waitcnt vmcnt(63)
	v_add_f32_e32 v250, v28, v156
	v_lshlrev_b32_e32 v102, 16, v102
	v_mul_f32_e32 v102, v250, v102
	v_cvt_pk_bf16_f32 v102, v102, v17
	v_add_f32_e32 v251, v44, v156
	v_lshlrev_b32_e32 v103, 16, v103
	v_mul_f32_e32 v103, v251, v103
	v_cvt_pk_bf16_f32 v103, v103, v17
	s_waitcnt vmcnt(60)
	v_add_f32_e32 v250, v29, v157
	v_lshlrev_b32_e32 v104, 16, v104
	v_mul_f32_e32 v104, v250, v104
	v_cvt_pk_bf16_f32 v104, v104, v17
	v_add_f32_e32 v251, v45, v157
	v_lshlrev_b32_e32 v105, 16, v105
	v_mul_f32_e32 v105, v251, v105
	v_cvt_pk_bf16_f32 v105, v105, v17
	s_waitcnt vmcnt(57)
	v_add_f32_e32 v250, v30, v158
	v_lshlrev_b32_e32 v106, 16, v106
	v_mul_f32_e32 v106, v250, v106
	v_cvt_pk_bf16_f32 v106, v106, v17
	v_add_f32_e32 v251, v46, v158
	v_lshlrev_b32_e32 v107, 16, v107
	v_mul_f32_e32 v107, v251, v107
	v_cvt_pk_bf16_f32 v107, v107, v17
	s_waitcnt vmcnt(54)
	v_add_f32_e32 v250, v31, v159
	v_lshlrev_b32_e32 v108, 16, v108
	v_mul_f32_e32 v108, v250, v108
	v_cvt_pk_bf16_f32 v108, v108, v17
	v_add_f32_e32 v251, v47, v159
	v_lshlrev_b32_e32 v109, 16, v109
	v_mul_f32_e32 v109, v251, v109
	v_cvt_pk_bf16_f32 v109, v109, v17
	s_waitcnt vmcnt(51)
	v_add_f32_e32 v250, v32, v160
	v_lshlrev_b32_e32 v110, 16, v110
	v_mul_f32_e32 v110, v250, v110
	v_cvt_pk_bf16_f32 v110, v110, v17
	v_add_f32_e32 v251, v48, v160
	v_lshlrev_b32_e32 v111, 16, v111
	v_mul_f32_e32 v111, v251, v111
	v_cvt_pk_bf16_f32 v111, v111, v17
	s_waitcnt vmcnt(48)
	v_add_f32_e32 v250, v33, v161
	v_lshlrev_b32_e32 v112, 16, v112
	v_mul_f32_e32 v112, v250, v112
	v_cvt_pk_bf16_f32 v112, v112, v17
	v_add_f32_e32 v251, v49, v161
	v_lshlrev_b32_e32 v113, 16, v113
	v_mul_f32_e32 v113, v251, v113
	v_cvt_pk_bf16_f32 v113, v113, v17
	s_waitcnt vmcnt(45)
	v_add_f32_e32 v250, v50, v234
	v_lshlrev_b32_e32 v114, 16, v114
	v_mul_f32_e32 v114, v250, v114
	v_cvt_pk_bf16_f32 v114, v114, v17
	v_add_f32_e32 v251, v66, v234
	v_lshlrev_b32_e32 v115, 16, v115
	v_mul_f32_e32 v115, v251, v115
	v_cvt_pk_bf16_f32 v115, v115, v17
	s_waitcnt vmcnt(42)
	v_add_f32_e32 v250, v51, v235
	v_lshlrev_b32_e32 v116, 16, v116
	v_mul_f32_e32 v116, v250, v116
	v_cvt_pk_bf16_f32 v116, v116, v17
	v_add_f32_e32 v251, v67, v235
	v_lshlrev_b32_e32 v117, 16, v117
	v_mul_f32_e32 v117, v251, v117
	v_cvt_pk_bf16_f32 v117, v117, v17
	s_waitcnt vmcnt(39)
	v_add_f32_e32 v250, v52, v236
	v_lshlrev_b32_e32 v118, 16, v118
	v_mul_f32_e32 v118, v250, v118
	v_cvt_pk_bf16_f32 v118, v118, v17
	v_add_f32_e32 v251, v68, v236
	v_lshlrev_b32_e32 v119, 16, v119
	v_mul_f32_e32 v119, v251, v119
	v_cvt_pk_bf16_f32 v119, v119, v17
	s_waitcnt vmcnt(36)
	v_add_f32_e32 v250, v53, v237
	v_lshlrev_b32_e32 v120, 16, v120
	v_mul_f32_e32 v120, v250, v120
	v_cvt_pk_bf16_f32 v120, v120, v17
	v_add_f32_e32 v251, v69, v237
	v_lshlrev_b32_e32 v121, 16, v121
	v_mul_f32_e32 v121, v251, v121
	v_cvt_pk_bf16_f32 v121, v121, v17
	s_waitcnt vmcnt(33)
; __device__ __forceinline__ unsigned short bf1(float a) { return (unsigned short)(cvtpk(a, 0.f) & 0xffffu); }
; __device__ __forceinline__ int crow(int r, int hi) { return (r & 3) + 8 * (r >> 2) + 4 * hi; }
; __device__ __forceinline__ void gmlp_item(PARAMS_T& p, int l, int b, int pos0, int tokrow0) {
;     ...
;   for (int tb = 0; tb < 2; ++tb)
; #pragma unroll
;     for (int r = 0; r < 16; ++r) {
;       const int t = th * 64 + tb * 32 + crow(r, hi);
;       const float bt = bs[t];
; #pragma unroll
;       for (int db = 0; db < 2; ++db) {
;         const int d = g * 64 + db * 32 + r32;
;         const float uv = __uint_as_float(((unsigned)u[(size_t)(tokrow0 + t) * 256 + d]) << 16);
;         outp[(size_t)(tokrow0 + t) * 1024 + 256 + d] = bf1(uv * (acc[tb][db][r] + bt));
	v_add_f32_e32 v250, v54, v238
	v_lshlrev_b32_e32 v122, 16, v122
	v_mul_f32_e32 v122, v250, v122
	v_cvt_pk_bf16_f32 v122, v122, v17
	v_add_f32_e32 v251, v70, v238
	v_lshlrev_b32_e32 v123, 16, v123
	v_mul_f32_e32 v123, v251, v123
	v_cvt_pk_bf16_f32 v123, v123, v17
	s_waitcnt vmcnt(30)
	v_add_f32_e32 v250, v55, v239
	v_lshlrev_b32_e32 v124, 16, v124
	v_mul_f32_e32 v124, v250, v124
	v_cvt_pk_bf16_f32 v124, v124, v17
	v_add_f32_e32 v251, v71, v239
	v_lshlrev_b32_e32 v125, 16, v125
	v_mul_f32_e32 v125, v251, v125
	v_cvt_pk_bf16_f32 v125, v125, v17
	s_waitcnt vmcnt(27)
	v_add_f32_e32 v250, v56, v240
	v_lshlrev_b32_e32 v126, 16, v126
	v_mul_f32_e32 v126, v250, v126
	v_cvt_pk_bf16_f32 v126, v126, v17
	v_add_f32_e32 v251, v72, v240
	v_lshlrev_b32_e32 v127, 16, v127
	v_mul_f32_e32 v127, v251, v127
	v_cvt_pk_bf16_f32 v127, v127, v17
	s_waitcnt vmcnt(24)
	v_add_f32_e32 v250, v57, v241
	v_lshlrev_b32_e32 v128, 16, v128
	v_mul_f32_e32 v128, v250, v128
	v_cvt_pk_bf16_f32 v128, v128, v17
	v_add_f32_e32 v251, v73, v241
	v_lshlrev_b32_e32 v129, 16, v129
	v_mul_f32_e32 v129, v251, v129
	v_cvt_pk_bf16_f32 v129, v129, v17
	s_waitcnt vmcnt(21)
	v_add_f32_e32 v250, v58, v242
	v_lshlrev_b32_e32 v130, 16, v130
	v_mul_f32_e32 v130, v250, v130
	v_cvt_pk_bf16_f32 v130, v130, v17
	v_add_f32_e32 v251, v74, v242
	v_lshlrev_b32_e32 v131, 16, v131
	v_mul_f32_e32 v131, v251, v131
	v_cvt_pk_bf16_f32 v131, v131, v17
	s_waitcnt vmcnt(18)
	v_add_f32_e32 v250, v59, v243
	v_lshlrev_b32_e32 v132, 16, v132
	v_mul_f32_e32 v132, v250, v132
	v_cvt_pk_bf16_f32 v132, v132, v17
	v_add_f32_e32 v251, v75, v243
	v_lshlrev_b32_e32 v133, 16, v133
	v_mul_f32_e32 v133, v251, v133
	v_cvt_pk_bf16_f32 v133, v133, v17
	s_waitcnt vmcnt(15)
	v_add_f32_e32 v250, v60, v244
	v_lshlrev_b32_e32 v134, 16, v134
	v_mul_f32_e32 v134, v250, v134
	v_cvt_pk_bf16_f32 v134, v134, v17
	v_add_f32_e32 v251, v76, v244
	v_lshlrev_b32_e32 v135, 16, v135
	v_mul_f32_e32 v135, v251, v135
	v_cvt_pk_bf16_f32 v135, v135, v17
	s_waitcnt vmcnt(12)
	v_add_f32_e32 v250, v61, v245
	v_lshlrev_b32_e32 v136, 16, v136
	v_mul_f32_e32 v136, v250, v136
	v_cvt_pk_bf16_f32 v136, v136, v17
	v_add_f32_e32 v251, v77, v245
	v_lshlrev_b32_e32 v137, 16, v137
	v_mul_f32_e32 v137, v251, v137
	v_cvt_pk_bf16_f32 v137, v137, v17
	s_waitcnt vmcnt(9)
	v_add_f32_e32 v250, v62, v246
	v_lshlrev_b32_e32 v138, 16, v138
	v_mul_f32_e32 v138, v250, v138
	v_cvt_pk_bf16_f32 v138, v138, v17
	v_add_f32_e32 v251, v78, v246
	v_lshlrev_b32_e32 v139, 16, v139
	v_mul_f32_e32 v139, v251, v139
	v_cvt_pk_bf16_f32 v139, v139, v17
	s_waitcnt vmcnt(6)
	v_add_f32_e32 v250, v63, v247
	v_lshlrev_b32_e32 v140, 16, v140
	v_mul_f32_e32 v140, v250, v140
	v_cvt_pk_bf16_f32 v140, v140, v17
	v_add_f32_e32 v251, v79, v247
	v_lshlrev_b32_e32 v141, 16, v141
	v_mul_f32_e32 v141, v251, v141
	v_cvt_pk_bf16_f32 v141, v141, v17
	s_waitcnt vmcnt(3)
	v_add_f32_e32 v250, v64, v248
	v_lshlrev_b32_e32 v142, 16, v142
	v_mul_f32_e32 v142, v250, v142
	v_cvt_pk_bf16_f32 v142, v142, v17
	v_add_f32_e32 v251, v80, v248
	v_lshlrev_b32_e32 v143, 16, v143
	v_mul_f32_e32 v143, v251, v143
	v_cvt_pk_bf16_f32 v143, v143, v17
	s_waitcnt vmcnt(0)
; __device__ __forceinline__ unsigned short bf1(float a) { return (unsigned short)(cvtpk(a, 0.f) & 0xffffu); }
; __device__ __forceinline__ int crow(int r, int hi) { return (r & 3) + 8 * (r >> 2) + 4 * hi; }
; __device__ __forceinline__ void gmlp_item(PARAMS_T& p, int l, int b, int pos0, int tokrow0) {
;     ...
;   for (int tb = 0; tb < 2; ++tb)
; #pragma unroll
;     for (int r = 0; r < 16; ++r) {
;       const int t = th * 64 + tb * 32 + crow(r, hi);
;       const float bt = bs[t];
; #pragma unroll
;       for (int db = 0; db < 2; ++db) {
;         const int d = g * 64 + db * 32 + r32;
;         const float uv = __uint_as_float(((unsigned)u[(size_t)(tokrow0 + t) * 256 + d]) << 16);
;         outp[(size_t)(tokrow0 + t) * 1024 + 256 + d] = bf1(uv * (acc[tb][db][r] + bt));
	v_add_f32_e32 v250, v65, v249
	v_lshlrev_b32_e32 v144, 16, v144
	v_mul_f32_e32 v144, v250, v144
	v_cvt_pk_bf16_f32 v144, v144, v17
	v_add_f32_e32 v251, v81, v249
	v_lshlrev_b32_e32 v145, 16, v145
	v_mul_f32_e32 v145, v251, v145
	v_cvt_pk_bf16_f32 v145, v145, v17
	v_add_u32_e32 v254, 0, v171
	v_lshl_add_u32 v146, v254, 11, v172
	v_add_u32_e32 v254, 2, v171
	v_lshl_add_u32 v147, v254, 11, v172
	v_add_u32_e32 v254, 8, v171
	v_lshl_add_u32 v148, v254, 11, v172
	v_add_u32_e32 v254, 10, v171
	v_lshl_add_u32 v149, v254, 11, v172
	v_add_u32_e32 v254, 16, v171
	v_lshl_add_u32 v150, v254, 11, v172
	v_add_u32_e32 v254, 18, v171
	v_lshl_add_u32 v151, v254, 11, v172
	v_add_u32_e32 v254, 24, v171
	v_lshl_add_u32 v152, v254, 11, v172
	v_add_u32_e32 v254, 26, v171
	v_lshl_add_u32 v153, v254, 11, v172
	v_add_u32_e32 v254, 32, v171
	v_lshl_add_u32 v154, v254, 11, v172
	v_add_u32_e32 v254, 34, v171
	v_lshl_add_u32 v155, v254, 11, v172
	v_add_u32_e32 v254, 40, v171
	v_lshl_add_u32 v156, v254, 11, v172
	v_add_u32_e32 v254, 42, v171
	v_lshl_add_u32 v157, v254, 11, v172
	v_add_u32_e32 v254, 48, v171
	v_lshl_add_u32 v158, v254, 11, v172
	v_add_u32_e32 v254, 50, v171
	v_lshl_add_u32 v159, v254, 11, v172
	v_add_u32_e32 v254, 56, v171
	v_lshl_add_u32 v160, v254, 11, v172
	v_add_u32_e32 v254, 58, v171
	v_lshl_add_u32 v161, v254, 11, v172
	global_store_short v146, v82, s[0:1]
	global_store_short v146, v83, s[0:1] offset:64
	global_store_short v146, v84, s[0:1] offset:2048
	global_store_short v146, v85, s[0:1] offset:2112
	global_store_short v147, v86, s[0:1]
	global_store_short v147, v87, s[0:1] offset:64
	global_store_short v147, v88, s[0:1] offset:2048
	global_store_short v147, v89, s[0:1] offset:2112
	global_store_short v148, v90, s[0:1]
	global_store_short v148, v91, s[0:1] offset:64
	global_store_short v148, v92, s[0:1] offset:2048
	global_store_short v148, v93, s[0:1] offset:2112
	global_store_short v149, v94, s[0:1]
	global_store_short v149, v95, s[0:1] offset:64
	global_store_short v149, v96, s[0:1] offset:2048
	global_store_short v149, v97, s[0:1] offset:2112
	global_store_short v150, v98, s[0:1]
	global_store_short v150, v99, s[0:1] offset:64
	global_store_short v150, v100, s[0:1] offset:2048
	global_store_short v150, v101, s[0:1] offset:2112
	global_store_short v151, v102, s[0:1]
	global_store_short v151, v103, s[0:1] offset:64
	global_store_short v151, v104, s[0:1] offset:2048
	global_store_short v151, v105, s[0:1] offset:2112
	global_store_short v152, v106, s[0:1]
	global_store_short v152, v107, s[0:1] offset:64
	global_store_short v152, v108, s[0:1] offset:2048
	global_store_short v152, v109, s[0:1] offset:2112
	global_store_short v153, v110, s[0:1]
	global_store_short v153, v111, s[0:1] offset:64
	global_store_short v153, v112, s[0:1] offset:2048
	global_store_short v153, v113, s[0:1] offset:2112
	global_store_short v154, v114, s[0:1]
	global_store_short v154, v115, s[0:1] offset:64
	global_store_short v154, v116, s[0:1] offset:2048
	global_store_short v154, v117, s[0:1] offset:2112
	global_store_short v155, v118, s[0:1]
	global_store_short v155, v119, s[0:1] offset:64
	global_store_short v155, v120, s[0:1] offset:2048
	global_store_short v155, v121, s[0:1] offset:2112
	global_store_short v156, v122, s[0:1]
	global_store_short v156, v123, s[0:1] offset:64
	global_store_short v156, v124, s[0:1] offset:2048
	global_store_short v156, v125, s[0:1] offset:2112
	global_store_short v157, v126, s[0:1]
	global_store_short v157, v127, s[0:1] offset:64
	global_store_short v157, v128, s[0:1] offset:2048
	global_store_short v157, v129, s[0:1] offset:2112
	global_store_short v158, v130, s[0:1]
	global_store_short v158, v131, s[0:1] offset:64
	global_store_short v158, v132, s[0:1] offset:2048
	global_store_short v158, v133, s[0:1] offset:2112
	global_store_short v159, v134, s[0:1]
	global_store_short v159, v135, s[0:1] offset:64
	global_store_short v159, v136, s[0:1] offset:2048
	global_store_short v159, v137, s[0:1] offset:2112
	global_store_short v160, v138, s[0:1]
	global_store_short v160, v139, s[0:1] offset:64
	global_store_short v160, v140, s[0:1] offset:2048
	global_store_short v160, v141, s[0:1] offset:2112
	global_store_short v161, v142, s[0:1]
	global_store_short v161, v143, s[0:1] offset:64
	global_store_short v161, v144, s[0:1] offset:2048
	global_store_short v161, v145, s[0:1] offset:2112
	s_mov_b64 s[4:5], 0

; __device__ __forceinline__ void gmlp_item(PARAMS_T& p, int l, int b, int pos0, int tokrow0) {
;     ...
;   {
;     const int dim = tid >> 1, half = tid & 1;
;     const float gd = p.gm_v_g[l * 256 + dim];
;     const unsigned short* src = (const unsigned short*)(p.ws + OFF_VT) + ((size_t)b * 256 + dim) * PTOK + pos0 + half * 64;
; #pragma unroll
;     for (int i = 0; i < 8; ++i) {
;       u32x4 w = *reinterpret_cast<const u32x4*>(src + i * 8);
;       const int t0 = half * 64 + i * 8;
;       float f0 = __uint_as_float(w[0] << 16) * rs[t0 + 0] * gd, f1 = __uint_as_float(w[0] & 0xffff0000u) * rs[t0 + 1] * gd;
;       float f2 = __uint_as_float(w[1] << 16) * rs[t0 + 2] * gd, f3 = __uint_as_float(w[1] & 0xffff0000u) * rs[t0 + 3] * gd;
;       float f4 = __uint_as_float(w[2] << 16) * rs[t0 + 4] * gd, f5 = __uint_as_float(w[2] & 0xffff0000u) * rs[t0 + 5] * gd;
;       float f6 = __uint_as_float(w[3] << 16) * rs[t0 + 6] * gd, f7 = __uint_as_float(w[3] & 0xffff0000u) * rs[t0 + 7] * gd;
;       u32x4 o = {cvtpk(f0, f1), cvtpk(f2, f3), cvtpk(f4, f5), cvtpk(f6, f7)};
;       *reinterpret_cast<u32x4*>(Vn + dim * 136 + t0) = o;
;     }
;   }
.LBB0_1887:
	s_or_b64 exec, exec, s[6:7]
	v_ashrrev_i32_e32 v34, 1, v20
	v_ashrrev_i32_e32 v35, 31, v34
	s_lshl_b64 s[6:7], s[80:81], 8
	v_lshl_add_u64 v[18:19], s[6:7], 0, v[34:35]
	v_readlane_b32 s6, v255, 24
	v_readlane_b32 s7, v255, 25
	s_movk_i32 s5, 0x4200
	v_lshlrev_b32_e32 v16, 6, v20
	v_mov_b64_e32 v[22:23], s[6:7]
	v_mad_u64_u32 v[22:23], s[6:7], v18, s5, v[22:23]
	v_mad_i32_i24 v23, v19, s5, v23
	s_lshl_b32 s80, s4, 1
	v_and_b32_e32 v21, 64, v16
	v_lshl_add_u64 v[18:19], v[22:23], 0, s[80:81]
	v_lshlrev_b32_e32 v16, 1, v21
	v_lshl_add_u64 v[18:19], v[18:19], 0, v[16:17]
	s_waitcnt lgkmcnt(0)
	s_barrier
	global_load_dwordx4 v[22:25], v[18:19], off
	s_load_dwordx2 s[4:5], s[0:1], 0x58
	s_load_dwordx2 s[6:7], s[0:1], 0x68
	v_lshl_add_u32 v36, v21, 2, 0
	v_readlane_b32 s8, v255, 38
	v_bfe_u32 v73, v20, 5, 1
	s_waitcnt lgkmcnt(0)
	v_lshl_add_u64 v[26:27], v[34:35], 2, s[4:5]
	global_load_dword v35, v[26:27], off offset:1024
	ds_read_b128 v[26:29], v36
	ds_read_b128 v[30:33], v36 offset:16
	s_movk_i32 s4, 0x110
	v_bfe_u32 v76, v20, 6, 1
	v_readlane_b32 s9, v255, 39
	v_mov_b32_e32 v79, v17
	s_waitcnt vmcnt(1)
	v_lshlrev_b32_e32 v21, 16, v22
	v_and_b32_e32 v22, 0xffff0000, v22
	v_lshlrev_b32_e32 v37, 16, v23
	v_and_b32_e32 v23, 0xffff0000, v23
	v_lshlrev_b32_e32 v38, 16, v24
	v_and_b32_e32 v24, 0xffff0000, v24
	v_lshlrev_b32_e32 v39, 16, v25
	v_and_b32_e32 v25, 0xffff0000, v25
	s_waitcnt lgkmcnt(1)
	v_mul_f32_e32 v21, v26, v21
	v_mul_f32_e32 v22, v27, v22
	v_mul_f32_e32 v26, v28, v37
	v_mul_f32_e32 v23, v29, v23
	s_waitcnt lgkmcnt(0)
	v_mul_f32_e32 v27, v30, v38
	v_mul_f32_e32 v24, v31, v24
	v_mul_f32_e32 v28, v32, v39
	v_mul_f32_e32 v25, v33, v25
	s_waitcnt vmcnt(0)
	v_mul_f32_e32 v22, v35, v22
	v_mul_f32_e32 v26, v35, v26
	v_mul_f32_e32 v23, v35, v23
	v_mul_f32_e32 v27, v35, v27
	v_mul_f32_e32 v24, v35, v24
	v_mul_f32_e32 v28, v35, v28
	v_mul_f32_e32 v25, v35, v25
	v_mul_f32_e32 v21, v35, v21
	v_cvt_pk_bf16_f32 v22, v21, v22
	v_cvt_pk_bf16_f32 v23, v26, v23
	v_cvt_pk_bf16_f32 v24, v27, v24
	v_cvt_pk_bf16_f32 v25, v28, v25
	global_load_dwordx4 v[26:29], v[18:19], off offset:16
	v_mul_lo_u32 v21, v34, s4
	v_add3_u32 v34, 0, v21, v16
	ds_write_b128 v34, v[22:25] offset:1024
	ds_read_b128 v[22:25], v36 offset:32
	ds_read_b128 v[30:33], v36 offset:48
	s_waitcnt vmcnt(0)
	v_lshlrev_b32_e32 v16, 16, v26
	v_and_b32_e32 v21, 0xffff0000, v26
	v_lshlrev_b32_e32 v26, 16, v27
	v_and_b32_e32 v27, 0xffff0000, v27
	v_lshlrev_b32_e32 v37, 16, v28
	v_and_b32_e32 v28, 0xffff0000, v28
	v_lshlrev_b32_e32 v38, 16, v29
	v_and_b32_e32 v29, 0xffff0000, v29
	s_waitcnt lgkmcnt(1)
	v_mul_f32_e32 v16, v22, v16
	v_mul_f32_e32 v21, v23, v21
	v_mul_f32_e32 v22, v24, v26
	v_mul_f32_e32 v23, v25, v27
	s_waitcnt lgkmcnt(0)
	v_mul_f32_e32 v24, v30, v37
	v_mul_f32_e32 v25, v31, v28
	v_mul_f32_e32 v26, v32, v38
	v_mul_f32_e32 v27, v33, v29
	v_mul_f32_e32 v28, v35, v22
	v_mul_f32_e32 v23, v35, v23
	v_mul_f32_e32 v24, v35, v24
	v_mul_f32_e32 v25, v35, v25
	v_mul_f32_e32 v26, v35, v26
	v_mul_f32_e32 v27, v35, v27
	v_mul_f32_e32 v16, v35, v16
	v_mul_f32_e32 v21, v35, v21
	v_cvt_pk_bf16_f32 v22, v16, v21
	v_cvt_pk_bf16_f32 v23, v28, v23
	v_cvt_pk_bf16_f32 v24, v24, v25
	v_cvt_pk_bf16_f32 v25, v26, v27
	global_load_dwordx4 v[26:29], v[18:19], off offset:32
	ds_write_b128 v34, v[22:25] offset:1040
	ds_read_b128 v[22:25], v36 offset:64
	ds_read_b128 v[30:33], v36 offset:80
	s_waitcnt vmcnt(0)
	v_lshlrev_b32_e32 v16, 16, v26
	v_and_b32_e32 v21, 0xffff0000, v26
	v_lshlrev_b32_e32 v26, 16, v27
	v_and_b32_e32 v27, 0xffff0000, v27
	v_lshlrev_b32_e32 v37, 16, v28
	v_and_b32_e32 v28, 0xffff0000, v28
	v_lshlrev_b32_e32 v38, 16, v29
	v_and_b32_e32 v29, 0xffff0000, v29
	s_waitcnt lgkmcnt(1)
	v_mul_f32_e32 v16, v22, v16
	v_mul_f32_e32 v21, v23, v21
	v_mul_f32_e32 v22, v24, v26
	v_mul_f32_e32 v23, v25, v27
	s_waitcnt lgkmcnt(0)
	v_mul_f32_e32 v24, v30, v37
	v_mul_f32_e32 v25, v31, v28
	v_mul_f32_e32 v26, v32, v38
	v_mul_f32_e32 v27, v33, v29
	v_mul_f32_e32 v28, v35, v22
	v_mul_f32_e32 v23, v35, v23
	v_mul_f32_e32 v24, v35, v24
	v_mul_f32_e32 v25, v35, v25
	v_mul_f32_e32 v26, v35, v26
	v_mul_f32_e32 v27, v35, v27
	v_mul_f32_e32 v16, v35, v16
	v_mul_f32_e32 v21, v35, v21
	v_cvt_pk_bf16_f32 v22, v16, v21
	v_cvt_pk_bf16_f32 v23, v28, v23
	v_cvt_pk_bf16_f32 v24, v24, v25
	v_cvt_pk_bf16_f32 v25, v26, v27
	global_load_dwordx4 v[26:29], v[18:19], off offset:48
	ds_write_b128 v34, v[22:25] offset:1056
	ds_read_b128 v[22:25], v36 offset:96
	ds_read_b128 v[30:33], v36 offset:112
	s_waitcnt vmcnt(0)
	v_lshlrev_b32_e32 v16, 16, v26
	v_and_b32_e32 v21, 0xffff0000, v26
	v_lshlrev_b32_e32 v26, 16, v27
	v_and_b32_e32 v27, 0xffff0000, v27
	v_lshlrev_b32_e32 v37, 16, v28
	v_and_b32_e32 v28, 0xffff0000, v28
	v_lshlrev_b32_e32 v38, 16, v29
	v_and_b32_e32 v29, 0xffff0000, v29
	s_waitcnt lgkmcnt(1)
	v_mul_f32_e32 v16, v22, v16
	v_mul_f32_e32 v21, v23, v21
	v_mul_f32_e32 v22, v24, v26
	v_mul_f32_e32 v23, v25, v27
	s_waitcnt lgkmcnt(0)
	v_mul_f32_e32 v24, v30, v37
	v_mul_f32_e32 v25, v31, v28
	v_mul_f32_e32 v26, v32, v38
	v_mul_f32_e32 v27, v33, v29
	v_mul_f32_e32 v28, v35, v22
	v_mul_f32_e32 v23, v35, v23
	v_mul_f32_e32 v24, v35, v24
	v_mul_f32_e32 v25, v35, v25
	v_mul_f32_e32 v26, v35, v26
	v_mul_f32_e32 v27, v35, v27
	v_mul_f32_e32 v16, v35, v16
	v_mul_f32_e32 v21, v35, v21
	v_cvt_pk_bf16_f32 v22, v16, v21
	v_cvt_pk_bf16_f32 v23, v28, v23
	v_cvt_pk_bf16_f32 v24, v24, v25
	v_cvt_pk_bf16_f32 v25, v26, v27
	global_load_dwordx4 v[26:29], v[18:19], off offset:64
	ds_write_b128 v34, v[22:25] offset:1072
	ds_read_b128 v[22:25], v36 offset:128
	ds_read_b128 v[30:33], v36 offset:144
	s_waitcnt vmcnt(0)
; __device__ __forceinline__ void gmlp_item(PARAMS_T& p, int l, int b, int pos0, int tokrow0) {
;     ...
;     for (int i = 0; i < 8; ++i) {
;       u32x4 w = *reinterpret_cast<const u32x4*>(src + i * 8);
;       const int t0 = half * 64 + i * 8;
;       float f0 = __uint_as_float(w[0] << 16) * rs[t0 + 0] * gd, f1 = __uint_as_float(w[0] & 0xffff0000u) * rs[t0 + 1] * gd;
;       float f2 = __uint_as_float(w[1] << 16) * rs[t0 + 2] * gd, f3 = __uint_as_float(w[1] & 0xffff0000u) * rs[t0 + 3] * gd;
;       float f4 = __uint_as_float(w[2] << 16) * rs[t0 + 4] * gd, f5 = __uint_as_float(w[2] & 0xffff0000u) * rs[t0 + 5] * gd;
;       float f6 = __uint_as_float(w[3] << 16) * rs[t0 + 6] * gd, f7 = __uint_as_float(w[3] & 0xffff0000u) * rs[t0 + 7] * gd;
;       u32x4 o = {cvtpk(f0, f1), cvtpk(f2, f3), cvtpk(f4, f5), cvtpk(f6, f7)};
;       *reinterpret_cast<u32x4*>(Vn + dim * 136 + t0) = o;
;     }
;   }
;   __syncthreads();
	v_lshlrev_b32_e32 v16, 16, v26
	v_and_b32_e32 v21, 0xffff0000, v26
	v_lshlrev_b32_e32 v26, 16, v27
	v_and_b32_e32 v27, 0xffff0000, v27
	v_lshlrev_b32_e32 v37, 16, v28
	v_and_b32_e32 v28, 0xffff0000, v28
	v_lshlrev_b32_e32 v38, 16, v29
	v_and_b32_e32 v29, 0xffff0000, v29
	s_waitcnt lgkmcnt(1)
	v_mul_f32_e32 v16, v22, v16
	v_mul_f32_e32 v21, v23, v21
	v_mul_f32_e32 v22, v24, v26
	v_mul_f32_e32 v23, v25, v27
	s_waitcnt lgkmcnt(0)
	v_mul_f32_e32 v24, v30, v37
	v_mul_f32_e32 v25, v31, v28
	v_mul_f32_e32 v26, v32, v38
	v_mul_f32_e32 v27, v33, v29
	v_mul_f32_e32 v28, v35, v22
	v_mul_f32_e32 v23, v35, v23
	v_mul_f32_e32 v24, v35, v24
	v_mul_f32_e32 v25, v35, v25
	v_mul_f32_e32 v26, v35, v26
	v_mul_f32_e32 v27, v35, v27
	v_mul_f32_e32 v16, v35, v16
	v_mul_f32_e32 v21, v35, v21
	v_cvt_pk_bf16_f32 v22, v16, v21
	v_cvt_pk_bf16_f32 v23, v28, v23
	v_cvt_pk_bf16_f32 v24, v24, v25
	v_cvt_pk_bf16_f32 v25, v26, v27
	global_load_dwordx4 v[26:29], v[18:19], off offset:80
	ds_write_b128 v34, v[22:25] offset:1088
	ds_read_b128 v[22:25], v36 offset:160
	ds_read_b128 v[30:33], v36 offset:176
	s_waitcnt vmcnt(0)
	v_lshlrev_b32_e32 v16, 16, v26
	v_and_b32_e32 v21, 0xffff0000, v26
	v_lshlrev_b32_e32 v26, 16, v27
	v_and_b32_e32 v27, 0xffff0000, v27
	v_lshlrev_b32_e32 v37, 16, v28
	v_and_b32_e32 v28, 0xffff0000, v28
	v_lshlrev_b32_e32 v38, 16, v29
	v_and_b32_e32 v29, 0xffff0000, v29
	s_waitcnt lgkmcnt(1)
	v_mul_f32_e32 v16, v22, v16
	v_mul_f32_e32 v21, v23, v21
	v_mul_f32_e32 v22, v24, v26
	v_mul_f32_e32 v23, v25, v27
	s_waitcnt lgkmcnt(0)
	v_mul_f32_e32 v24, v30, v37
	v_mul_f32_e32 v25, v31, v28
	v_mul_f32_e32 v26, v32, v38
	v_mul_f32_e32 v27, v33, v29
	v_mul_f32_e32 v28, v35, v22
	v_mul_f32_e32 v23, v35, v23
	v_mul_f32_e32 v24, v35, v24
	v_mul_f32_e32 v25, v35, v25
	v_mul_f32_e32 v26, v35, v26
	v_mul_f32_e32 v27, v35, v27
	v_mul_f32_e32 v16, v35, v16
	v_mul_f32_e32 v21, v35, v21
	v_cvt_pk_bf16_f32 v22, v16, v21
	v_cvt_pk_bf16_f32 v23, v28, v23
	v_cvt_pk_bf16_f32 v24, v24, v25
	v_cvt_pk_bf16_f32 v25, v26, v27
	global_load_dwordx4 v[26:29], v[18:19], off offset:96
	ds_write_b128 v34, v[22:25] offset:1104
	ds_read_b128 v[22:25], v36 offset:192
	ds_read_b128 v[30:33], v36 offset:208
	s_waitcnt vmcnt(0)
	v_lshlrev_b32_e32 v16, 16, v26
	v_and_b32_e32 v21, 0xffff0000, v26
	v_lshlrev_b32_e32 v26, 16, v27
	v_and_b32_e32 v27, 0xffff0000, v27
	v_lshlrev_b32_e32 v37, 16, v28
	v_and_b32_e32 v28, 0xffff0000, v28
	v_lshlrev_b32_e32 v38, 16, v29
	v_and_b32_e32 v29, 0xffff0000, v29
	s_waitcnt lgkmcnt(1)
	v_mul_f32_e32 v16, v22, v16
	v_mul_f32_e32 v21, v23, v21
	v_mul_f32_e32 v22, v24, v26
	v_mul_f32_e32 v23, v25, v27
	s_waitcnt lgkmcnt(0)
	v_mul_f32_e32 v24, v30, v37
	v_mul_f32_e32 v25, v31, v28
	v_mul_f32_e32 v26, v32, v38
	v_mul_f32_e32 v27, v33, v29
	v_mul_f32_e32 v28, v35, v22
	v_mul_f32_e32 v23, v35, v23
	v_mul_f32_e32 v24, v35, v24
	v_mul_f32_e32 v25, v35, v25
	v_mul_f32_e32 v26, v35, v26
	v_mul_f32_e32 v27, v35, v27
	v_mul_f32_e32 v16, v35, v16
	v_mul_f32_e32 v21, v35, v21
	v_cvt_pk_bf16_f32 v22, v16, v21
	v_cvt_pk_bf16_f32 v23, v28, v23
	v_cvt_pk_bf16_f32 v24, v24, v25
	v_cvt_pk_bf16_f32 v25, v26, v27
	global_load_dwordx4 v[26:29], v[18:19], off offset:112
	v_ashrrev_i32_e32 v31, 7, v20
	v_add_u32_e32 v70, 4, v31
	v_and_b32_e32 v30, 31, v20
	v_ashrrev_i32_e32 v71, 31, v70
	v_lshlrev_b32_e32 v16, 8, v30
	v_lshlrev_b64 v[18:19], 15, v[70:71]
	v_lshl_or_b32 v78, v76, 14, v16
	v_lshl_add_u64 v[18:19], s[8:9], 0, v[18:19]
	v_lshlrev_b32_e32 v16, 4, v73
	ds_write_b128 v34, v[22:25] offset:1120
	v_lshl_add_u64 v[80:81], v[18:19], 0, v[16:17]
	ds_read_b128 v[18:21], v36 offset:224
	ds_read_b128 v[22:25], v36 offset:240
	v_lshl_add_u64 v[74:75], v[80:81], 0, v[78:79]
	v_lshl_or_b32 v72, v31, 6, v30
	v_lshlrev_b64 v[70:71], 9, v[70:71]
	s_waitcnt vmcnt(0)
	v_lshlrev_b32_e32 v32, 16, v26
	v_and_b32_e32 v26, 0xffff0000, v26
	v_lshlrev_b32_e32 v33, 16, v27
	v_and_b32_e32 v27, 0xffff0000, v27
	v_lshlrev_b32_e32 v36, 16, v28
	v_and_b32_e32 v28, 0xffff0000, v28
	v_lshlrev_b32_e32 v37, 16, v29
	v_and_b32_e32 v29, 0xffff0000, v29
	s_waitcnt lgkmcnt(1)
	v_mul_f32_e32 v18, v18, v32
	v_mul_f32_e32 v19, v19, v26
	v_mul_f32_e32 v20, v20, v33
	v_mul_f32_e32 v21, v21, v27
	s_waitcnt lgkmcnt(0)
	v_mul_f32_e32 v22, v22, v36
	v_mul_f32_e32 v23, v23, v28
	v_mul_f32_e32 v24, v24, v37
	v_mul_f32_e32 v25, v25, v29
	v_mul_f32_e32 v18, v35, v18
	v_mul_f32_e32 v19, v35, v19
	v_mul_f32_e32 v20, v35, v20
	v_mul_f32_e32 v21, v35, v21
	v_mul_f32_e32 v22, v35, v22
	v_mul_f32_e32 v23, v35, v23
	v_mul_f32_e32 v24, v35, v24
	v_mul_f32_e32 v25, v35, v25
	v_cvt_pk_bf16_f32 v18, v18, v19
	v_cvt_pk_bf16_f32 v19, v20, v21
	v_cvt_pk_bf16_f32 v20, v22, v23
	v_cvt_pk_bf16_f32 v21, v24, v25
	ds_write_b128 v34, v[18:21] offset:1136
	s_waitcnt lgkmcnt(0)
	s_barrier
; __device__ __forceinline__ void gmlp_item(PARAMS_T& p, int l, int b, int pos0, int tokrow0) {
;     ...
;   const int g = wid >> 1, th = wid & 1;
;   const bf16* wsb = (const bf16*)(p.ws + OFF_WSBF) + ((size_t)l * 4 + g) * 128 * 128;
;   f32x16 acc[2][2] = {};
; #pragma unroll
;   for (int ks = 0; ks < 8; ++ks) {
;     bf16x8 af[2], bfr[2];
; #pragma unroll
;     for (int tb = 0; tb < 2; ++tb) af[tb] = *reinterpret_cast<const bf16x8*>(wsb + (size_t)(th * 64 + tb * 32 + r32) * 128 + ks * 16 + hi * 8);
; #pragma unroll
;     for (int db = 0; db < 2; ++db) bfr[db] = *reinterpret_cast<const bf16x8*>(Vn + (g * 64 + db * 32 + r32) * 136 + ks * 16 + hi * 8);
; #pragma unroll
;     for (int tb = 0; tb < 2; ++tb)
; #pragma unroll
;       for (int db = 0; db < 2; ++db) acc[tb][db] = __builtin_amdgcn_mfma_f32_32x32x16_bf16(af[tb], bfr[db], acc[tb][db], 0, 0, 0);
;   }
	v_and_b32_e32 v250, 31, v192
	v_bfe_u32 v251, v192, 5, 1
	v_lshrrev_b32_e32 v252, 7, v192
	v_bfe_u32 v253, v192, 6, 1
	v_lshl_or_b32 v254, v252, 6, v250
	v_lshlrev_b32_e32 v172, 1, v254
	v_mul_u32_u24_e32 v254, 0x110, v254
	v_lshl_add_u32 v254, v251, 4, v254
	v_add_u32_e32 v16, 0x400, v254
	v_add_u32_e32 v252, 4, v252
	v_lshl_or_b32 v254, v253, 6, v250
	v_lshlrev_b32_e32 v254, 8, v254
	v_lshl_or_b32 v254, v251, 4, v254
	v_lshl_add_u32 v254, v252, 15, v254
	v_mov_b32_e32 v162, v254
	v_mov_b32_e32 v163, 0
	v_lshl_add_u64 v[162:163], s[8:9], 0, v[162:163]
	v_mov_b32_e32 v164, 0x2000
	v_mov_b32_e32 v165, 0
	v_lshl_add_u64 v[164:165], v[162:163], 0, v[164:165]
	global_load_dwordx4 v[82:85], v[162:163], off
	global_load_dwordx4 v[86:89], v[164:165], off
	global_load_dwordx4 v[90:93], v[162:163], off offset:32
	global_load_dwordx4 v[94:97], v[164:165], off offset:32
	global_load_dwordx4 v[98:101], v[162:163], off offset:64
	global_load_dwordx4 v[102:105], v[164:165], off offset:64
	global_load_dwordx4 v[106:109], v[162:163], off offset:96
	global_load_dwordx4 v[110:113], v[164:165], off offset:96
	global_load_dwordx4 v[114:117], v[162:163], off offset:128
	global_load_dwordx4 v[118:121], v[164:165], off offset:128
	global_load_dwordx4 v[122:125], v[162:163], off offset:160
	global_load_dwordx4 v[126:129], v[164:165], off offset:160
	global_load_dwordx4 v[130:133], v[162:163], off offset:192
	global_load_dwordx4 v[134:137], v[164:165], off offset:192
	global_load_dwordx4 v[138:141], v[162:163], off offset:224
	global_load_dwordx4 v[142:145], v[164:165], off offset:224
	v_lshlrev_b32_e32 v171, 6, v253
	v_lshl_add_u32 v171, v251, 2, v171
	v_lshl_add_u32 v170, v252, 7, v171
	v_lshlrev_b32_e32 v170, 2, v170
	v_add_u32_e32 v171, s3, v171
	v_add_u32_e32 v254, 0, v171
	v_lshl_add_u32 v162, v254, 9, v172
	v_add_u32_e32 v254, 8, v171
	v_lshl_add_u32 v163, v254, 9, v172
	v_add_u32_e32 v254, 16, v171
	v_lshl_add_u32 v164, v254, 9, v172
	v_add_u32_e32 v254, 24, v171
	v_lshl_add_u32 v165, v254, 9, v172
	v_add_u32_e32 v254, 32, v171
	v_lshl_add_u32 v166, v254, 9, v172
	v_add_u32_e32 v254, 40, v171
	v_lshl_add_u32 v167, v254, 9, v172
	v_add_u32_e32 v254, 48, v171
	v_lshl_add_u32 v168, v254, 9, v172
	v_add_u32_e32 v254, 56, v171
	v_lshl_add_u32 v169, v254, 9, v172
	v_mov_b32_e32 v18, 0
	v_mov_b32_e32 v19, 0
	v_mov_b32_e32 v20, 0
	v_mov_b32_e32 v21, 0
	v_mov_b32_e32 v22, 0
	v_mov_b32_e32 v23, 0
	v_mov_b32_e32 v24, 0
	v_mov_b32_e32 v25, 0
	v_mov_b32_e32 v26, 0
	v_mov_b32_e32 v27, 0
	v_mov_b32_e32 v28, 0
	v_mov_b32_e32 v29, 0
	v_mov_b32_e32 v30, 0
	v_mov_b32_e32 v31, 0
	v_mov_b32_e32 v32, 0
	v_mov_b32_e32 v33, 0
	v_mov_b32_e32 v34, 0
	v_mov_b32_e32 v35, 0
	v_mov_b32_e32 v36, 0
	v_mov_b32_e32 v37, 0
	v_mov_b32_e32 v38, 0
	v_mov_b32_e32 v39, 0
	v_mov_b32_e32 v40, 0
	v_mov_b32_e32 v41, 0
	v_mov_b32_e32 v42, 0
	v_mov_b32_e32 v43, 0
	v_mov_b32_e32 v44, 0
	v_mov_b32_e32 v45, 0
	v_mov_b32_e32 v46, 0
	v_mov_b32_e32 v47, 0
	v_mov_b32_e32 v48, 0
	v_mov_b32_e32 v49, 0
	v_mov_b32_e32 v50, 0
	v_mov_b32_e32 v51, 0
	v_mov_b32_e32 v52, 0
	v_mov_b32_e32 v53, 0
	v_mov_b32_e32 v54, 0
	v_mov_b32_e32 v55, 0
	v_mov_b32_e32 v56, 0
	v_mov_b32_e32 v57, 0
	v_mov_b32_e32 v58, 0
	v_mov_b32_e32 v59, 0
	v_mov_b32_e32 v60, 0
	v_mov_b32_e32 v61, 0
	v_mov_b32_e32 v62, 0
	v_mov_b32_e32 v63, 0
	v_mov_b32_e32 v64, 0
	v_mov_b32_e32 v65, 0
	v_mov_b32_e32 v66, 0
	v_mov_b32_e32 v67, 0
	v_mov_b32_e32 v68, 0
	v_mov_b32_e32 v69, 0
	v_mov_b32_e32 v70, 0
	v_mov_b32_e32 v71, 0
	v_mov_b32_e32 v72, 0
	v_mov_b32_e32 v73, 0
	v_mov_b32_e32 v74, 0
	v_mov_b32_e32 v75, 0
	v_mov_b32_e32 v76, 0
	v_mov_b32_e32 v77, 0
	v_mov_b32_e32 v78, 0
	v_mov_b32_e32 v79, 0
	v_mov_b32_e32 v80, 0
	v_mov_b32_e32 v81, 0
	ds_read_b128 v[146:149], v16 offset:0
	ds_read_b128 v[150:153], v16 offset:8704
	ds_read_b128 v[154:157], v16 offset:32
	ds_read_b128 v[158:161], v16 offset:8736
	ds_read_b128 v[234:237], v16 offset:64
	ds_read_b128 v[238:241], v16 offset:8768
	ds_read_b128 v[242:245], v16 offset:96
	ds_read_b128 v[246:249], v16 offset:8800
	s_waitcnt vmcnt(15) lgkmcnt(7)
	v_mfma_f32_32x32x16_bf16 v[18:33], v[82:85], v[146:149], v[18:33]
	s_waitcnt vmcnt(15) lgkmcnt(6)
	v_mfma_f32_32x32x16_bf16 v[34:49], v[82:85], v[150:153], v[34:49]
	s_waitcnt vmcnt(14)
	v_mfma_f32_32x32x16_bf16 v[50:65], v[86:89], v[146:149], v[50:65]
	v_mfma_f32_32x32x16_bf16 v[66:81], v[86:89], v[150:153], v[66:81]
	s_waitcnt vmcnt(13) lgkmcnt(5)
	v_mfma_f32_32x32x16_bf16 v[18:33], v[90:93], v[154:157], v[18:33]
	s_waitcnt vmcnt(13) lgkmcnt(4)
	v_mfma_f32_32x32x16_bf16 v[34:49], v[90:93], v[158:161], v[34:49]
	s_waitcnt vmcnt(12)
	v_mfma_f32_32x32x16_bf16 v[50:65], v[94:97], v[154:157], v[50:65]
	v_mfma_f32_32x32x16_bf16 v[66:81], v[94:97], v[158:161], v[66:81]
	s_waitcnt vmcnt(11) lgkmcnt(3)
	v_mfma_f32_32x32x16_bf16 v[18:33], v[98:101], v[234:237], v[18:33]
	s_waitcnt vmcnt(11) lgkmcnt(2)
	v_mfma_f32_32x32x16_bf16 v[34:49], v[98:101], v[238:241], v[34:49]
	s_waitcnt vmcnt(10)
	v_mfma_f32_32x32x16_bf16 v[50:65], v[102:105], v[234:237], v[50:65]
	v_mfma_f32_32x32x16_bf16 v[66:81], v[102:105], v[238:241], v[66:81]
	s_waitcnt vmcnt(9) lgkmcnt(1)
	v_mfma_f32_32x32x16_bf16 v[18:33], v[106:109], v[242:245], v[18:33]
	s_waitcnt vmcnt(9) lgkmcnt(0)
	v_mfma_f32_32x32x16_bf16 v[34:49], v[106:109], v[246:249], v[34:49]
	s_waitcnt vmcnt(8)
	v_mfma_f32_32x32x16_bf16 v[50:65], v[110:113], v[242:245], v[50:65]
	v_mfma_f32_32x32x16_bf16 v[66:81], v[110:113], v[246:249], v[66:81]
	ds_read_b128 v[146:149], v16 offset:128
	ds_read_b128 v[150:153], v16 offset:8832
	ds_read_b128 v[154:157], v16 offset:160
	ds_read_b128 v[158:161], v16 offset:8864
	ds_read_b128 v[234:237], v16 offset:192
	ds_read_b128 v[238:241], v16 offset:8896
	ds_read_b128 v[242:245], v16 offset:224
	ds_read_b128 v[246:249], v16 offset:8928
	s_waitcnt vmcnt(7) lgkmcnt(7)
; __device__ __forceinline__ unsigned short bf1(float a) { return (unsigned short)(cvtpk(a, 0.f) & 0xffffu); }
; __device__ __forceinline__ int crow(int r, int hi) { return (r & 3) + 8 * (r >> 2) + 4 * hi; }
; __device__ __forceinline__ void gmlp_item(PARAMS_T& p, int l, int b, int pos0, int tokrow0) {
;     ...
; #pragma unroll
;   for (int ks = 0; ks < 8; ++ks) {
;     bf16x8 af[2], bfr[2];
; #pragma unroll
;     for (int tb = 0; tb < 2; ++tb) af[tb] = *reinterpret_cast<const bf16x8*>(wsb + (size_t)(th * 64 + tb * 32 + r32) * 128 + ks * 16 + hi * 8);
; #pragma unroll
;     for (int db = 0; db < 2; ++db) bfr[db] = *reinterpret_cast<const bf16x8*>(Vn + (g * 64 + db * 32 + r32) * 136 + ks * 16 + hi * 8);
; #pragma unroll
;     for (int tb = 0; tb < 2; ++tb)
; #pragma unroll
;       for (int db = 0; db < 2; ++db) acc[tb][db] = __builtin_amdgcn_mfma_f32_32x32x16_bf16(af[tb], bfr[db], acc[tb][db], 0, 0, 0);
;   }
;   const float* bs = p.gm_bs + ((size_t)l * 4 + g) * 128;
;   const unsigned short* u = (const unsigned short*)(p.ws + OFF_U);
;   unsigned short* outp = (unsigned short*)(p.ws + OFF_ACTA);
; #pragma unroll
;   for (int tb = 0; tb < 2; ++tb)
; #pragma unroll
;     for (int r = 0; r < 16; ++r) {
;       const int t = th * 64 + tb * 32 + crow(r, hi);
;       const float bt = bs[t];
; #pragma unroll
;       for (int db = 0; db < 2; ++db) {
;         const int d = g * 64 + db * 32 + r32;
;         const float uv = __uint_as_float(((unsigned)u[(size_t)(tokrow0 + t) * 256 + d]) << 16);
;         outp[(size_t)(tokrow0 + t) * 1024 + 256 + d] = bf1(uv * (acc[tb][db][r] + bt));
	v_mfma_f32_32x32x16_bf16 v[18:33], v[114:117], v[146:149], v[18:33]
	s_waitcnt vmcnt(7) lgkmcnt(6)
	v_mfma_f32_32x32x16_bf16 v[34:49], v[114:117], v[150:153], v[34:49]
	s_waitcnt vmcnt(6)
	v_mfma_f32_32x32x16_bf16 v[50:65], v[118:121], v[146:149], v[50:65]
	v_mfma_f32_32x32x16_bf16 v[66:81], v[118:121], v[150:153], v[66:81]
	s_waitcnt vmcnt(5) lgkmcnt(5)
	v_mfma_f32_32x32x16_bf16 v[18:33], v[122:125], v[154:157], v[18:33]
	s_waitcnt vmcnt(5) lgkmcnt(4)
	v_mfma_f32_32x32x16_bf16 v[34:49], v[122:125], v[158:161], v[34:49]
	s_waitcnt vmcnt(4)
	v_mfma_f32_32x32x16_bf16 v[50:65], v[126:129], v[154:157], v[50:65]
	v_mfma_f32_32x32x16_bf16 v[66:81], v[126:129], v[158:161], v[66:81]
	s_waitcnt vmcnt(3) lgkmcnt(3)
	v_mfma_f32_32x32x16_bf16 v[18:33], v[130:133], v[234:237], v[18:33]
	s_waitcnt vmcnt(3) lgkmcnt(2)
	v_mfma_f32_32x32x16_bf16 v[34:49], v[130:133], v[238:241], v[34:49]
	s_waitcnt vmcnt(2)
	v_mfma_f32_32x32x16_bf16 v[50:65], v[134:137], v[234:237], v[50:65]
	v_mfma_f32_32x32x16_bf16 v[66:81], v[134:137], v[238:241], v[66:81]
	s_waitcnt vmcnt(1) lgkmcnt(1)
	v_mfma_f32_32x32x16_bf16 v[18:33], v[138:141], v[242:245], v[18:33]
	s_waitcnt vmcnt(1) lgkmcnt(0)
	v_mfma_f32_32x32x16_bf16 v[34:49], v[138:141], v[246:249], v[34:49]
	s_waitcnt vmcnt(0)
	v_mfma_f32_32x32x16_bf16 v[50:65], v[142:145], v[242:245], v[50:65]
	v_mfma_f32_32x32x16_bf16 v[66:81], v[142:145], v[246:249], v[66:81]
	global_load_ushort v82, v162, s[94:95]
	global_load_ushort v83, v162, s[94:95] offset:64
	global_load_dword v146, v170, s[6:7]
	global_load_ushort v84, v162, s[94:95] offset:512
	global_load_ushort v85, v162, s[94:95] offset:576
	global_load_dword v147, v170, s[6:7] offset:4
	global_load_ushort v86, v162, s[94:95] offset:1024
	global_load_ushort v87, v162, s[94:95] offset:1088
	global_load_dword v148, v170, s[6:7] offset:8
	global_load_ushort v88, v162, s[94:95] offset:1536
	global_load_ushort v89, v162, s[94:95] offset:1600
	global_load_dword v149, v170, s[6:7] offset:12
	global_load_ushort v90, v163, s[94:95]
	global_load_ushort v91, v163, s[94:95] offset:64
	global_load_dword v150, v170, s[6:7] offset:32
	global_load_ushort v92, v163, s[94:95] offset:512
	global_load_ushort v93, v163, s[94:95] offset:576
	global_load_dword v151, v170, s[6:7] offset:36
	global_load_ushort v94, v163, s[94:95] offset:1024
	global_load_ushort v95, v163, s[94:95] offset:1088
	global_load_dword v152, v170, s[6:7] offset:40
	global_load_ushort v96, v163, s[94:95] offset:1536
	global_load_ushort v97, v163, s[94:95] offset:1600
	global_load_dword v153, v170, s[6:7] offset:44
	global_load_ushort v98, v164, s[94:95]
	global_load_ushort v99, v164, s[94:95] offset:64
	global_load_dword v154, v170, s[6:7] offset:64
	global_load_ushort v100, v164, s[94:95] offset:512
	global_load_ushort v101, v164, s[94:95] offset:576
	global_load_dword v155, v170, s[6:7] offset:68
	global_load_ushort v102, v164, s[94:95] offset:1024
	global_load_ushort v103, v164, s[94:95] offset:1088
	global_load_dword v156, v170, s[6:7] offset:72
	global_load_ushort v104, v164, s[94:95] offset:1536
	global_load_ushort v105, v164, s[94:95] offset:1600
	global_load_dword v157, v170, s[6:7] offset:76
	global_load_ushort v106, v165, s[94:95]
	global_load_ushort v107, v165, s[94:95] offset:64
	global_load_dword v158, v170, s[6:7] offset:96
	global_load_ushort v108, v165, s[94:95] offset:512
	global_load_ushort v109, v165, s[94:95] offset:576
	global_load_dword v159, v170, s[6:7] offset:100
	global_load_ushort v110, v165, s[94:95] offset:1024
	global_load_ushort v111, v165, s[94:95] offset:1088
	global_load_dword v160, v170, s[6:7] offset:104
	global_load_ushort v112, v165, s[94:95] offset:1536
	global_load_ushort v113, v165, s[94:95] offset:1600
	global_load_dword v161, v170, s[6:7] offset:108
	global_load_ushort v114, v166, s[94:95]
	global_load_ushort v115, v166, s[94:95] offset:64
	global_load_dword v234, v170, s[6:7] offset:128
	global_load_ushort v116, v166, s[94:95] offset:512
	global_load_ushort v117, v166, s[94:95] offset:576
	global_load_dword v235, v170, s[6:7] offset:132
	global_load_ushort v118, v166, s[94:95] offset:1024
	global_load_ushort v119, v166, s[94:95] offset:1088
	global_load_dword v236, v170, s[6:7] offset:136
	global_load_ushort v120, v166, s[94:95] offset:1536
	global_load_ushort v121, v166, s[94:95] offset:1600
	global_load_dword v237, v170, s[6:7] offset:140
	global_load_ushort v122, v167, s[94:95]
	global_load_ushort v123, v167, s[94:95] offset:64
	global_load_dword v238, v170, s[6:7] offset:160
	global_load_ushort v124, v167, s[94:95] offset:512
	global_load_ushort v125, v167, s[94:95] offset:576
	global_load_dword v239, v170, s[6:7] offset:164
	global_load_ushort v126, v167, s[94:95] offset:1024
	global_load_ushort v127, v167, s[94:95] offset:1088
	global_load_dword v240, v170, s[6:7] offset:168
	global_load_ushort v128, v167, s[94:95] offset:1536
	global_load_ushort v129, v167, s[94:95] offset:1600
	global_load_dword v241, v170, s[6:7] offset:172
	global_load_ushort v130, v168, s[94:95]
	global_load_ushort v131, v168, s[94:95] offset:64
	global_load_dword v242, v170, s[6:7] offset:192
	global_load_ushort v132, v168, s[94:95] offset:512
	global_load_ushort v133, v168, s[94:95] offset:576
	global_load_dword v243, v170, s[6:7] offset:196
	global_load_ushort v134, v168, s[94:95] offset:1024
	global_load_ushort v135, v168, s[94:95] offset:1088
	global_load_dword v244, v170, s[6:7] offset:200
	global_load_ushort v136, v168, s[94:95] offset:1536
	global_load_ushort v137, v168, s[94:95] offset:1600
	global_load_dword v245, v170, s[6:7] offset:204
	global_load_ushort v138, v169, s[94:95]
	global_load_ushort v139, v169, s[94:95] offset:64
	global_load_dword v246, v170, s[6:7] offset:224
	global_load_ushort v140, v169, s[94:95] offset:512
	global_load_ushort v141, v169, s[94:95] offset:576
	global_load_dword v247, v170, s[6:7] offset:228
	global_load_ushort v142, v169, s[94:95] offset:1024
	global_load_ushort v143, v169, s[94:95] offset:1088
	global_load_dword v248, v170, s[6:7] offset:232
	global_load_ushort v144, v169, s[94:95] offset:1536
	global_load_ushort v145, v169, s[94:95] offset:1600
	global_load_dword v249, v170, s[6:7] offset:236
	s_waitcnt vmcnt(63)
; __device__ __forceinline__ unsigned short bf1(float a) { return (unsigned short)(cvtpk(a, 0.f) & 0xffffu); }
; __device__ __forceinline__ int crow(int r, int hi) { return (r & 3) + 8 * (r >> 2) + 4 * hi; }
; __device__ __forceinline__ void gmlp_item(PARAMS_T& p, int l, int b, int pos0, int tokrow0) {
;     ...
; #pragma unroll
;   for (int tb = 0; tb < 2; ++tb)
; #pragma unroll
;     for (int r = 0; r < 16; ++r) {
;       const int t = th * 64 + tb * 32 + crow(r, hi);
;       const float bt = bs[t];
; #pragma unroll
;       for (int db = 0; db < 2; ++db) {
;         const int d = g * 64 + db * 32 + r32;
;         const float uv = __uint_as_float(((unsigned)u[(size_t)(tokrow0 + t) * 256 + d]) << 16);
;         outp[(size_t)(tokrow0 + t) * 1024 + 256 + d] = bf1(uv * (acc[tb][db][r] + bt));
;       }
	v_add_f32_e32 v250, v18, v146
	v_lshlrev_b32_e32 v82, 16, v82
	v_mul_f32_e32 v82, v250, v82
	v_cvt_pk_bf16_f32 v82, v82, v17
	v_add_f32_e32 v251, v34, v146
	v_lshlrev_b32_e32 v83, 16, v83
	v_mul_f32_e32 v83, v251, v83
	v_cvt_pk_bf16_f32 v83, v83, v17
	s_waitcnt vmcnt(63)
	v_add_f32_e32 v250, v19, v147
	v_lshlrev_b32_e32 v84, 16, v84
	v_mul_f32_e32 v84, v250, v84
	v_cvt_pk_bf16_f32 v84, v84, v17
	v_add_f32_e32 v251, v35, v147
	v_lshlrev_b32_e32 v85, 16, v85
	v_mul_f32_e32 v85, v251, v85
	v_cvt_pk_bf16_f32 v85, v85, v17
	s_waitcnt vmcnt(63)
	v_add_f32_e32 v250, v20, v148
	v_lshlrev_b32_e32 v86, 16, v86
	v_mul_f32_e32 v86, v250, v86
	v_cvt_pk_bf16_f32 v86, v86, v17
	v_add_f32_e32 v251, v36, v148
	v_lshlrev_b32_e32 v87, 16, v87
	v_mul_f32_e32 v87, v251, v87
	v_cvt_pk_bf16_f32 v87, v87, v17
	s_waitcnt vmcnt(63)
	v_add_f32_e32 v250, v21, v149
	v_lshlrev_b32_e32 v88, 16, v88
	v_mul_f32_e32 v88, v250, v88
	v_cvt_pk_bf16_f32 v88, v88, v17
	v_add_f32_e32 v251, v37, v149
	v_lshlrev_b32_e32 v89, 16, v89
	v_mul_f32_e32 v89, v251, v89
	v_cvt_pk_bf16_f32 v89, v89, v17
	s_waitcnt vmcnt(63)
	v_add_f32_e32 v250, v22, v150
	v_lshlrev_b32_e32 v90, 16, v90
	v_mul_f32_e32 v90, v250, v90
	v_cvt_pk_bf16_f32 v90, v90, v17
	v_add_f32_e32 v251, v38, v150
	v_lshlrev_b32_e32 v91, 16, v91
	v_mul_f32_e32 v91, v251, v91
	v_cvt_pk_bf16_f32 v91, v91, v17
	s_waitcnt vmcnt(63)
	v_add_f32_e32 v250, v23, v151
	v_lshlrev_b32_e32 v92, 16, v92
	v_mul_f32_e32 v92, v250, v92
	v_cvt_pk_bf16_f32 v92, v92, v17
	v_add_f32_e32 v251, v39, v151
	v_lshlrev_b32_e32 v93, 16, v93
	v_mul_f32_e32 v93, v251, v93
	v_cvt_pk_bf16_f32 v93, v93, v17
	s_waitcnt vmcnt(63)
	v_add_f32_e32 v250, v24, v152
	v_lshlrev_b32_e32 v94, 16, v94
	v_mul_f32_e32 v94, v250, v94
	v_cvt_pk_bf16_f32 v94, v94, v17
	v_add_f32_e32 v251, v40, v152
	v_lshlrev_b32_e32 v95, 16, v95
	v_mul_f32_e32 v95, v251, v95
	v_cvt_pk_bf16_f32 v95, v95, v17
	s_waitcnt vmcnt(63)
	v_add_f32_e32 v250, v25, v153
	v_lshlrev_b32_e32 v96, 16, v96
	v_mul_f32_e32 v96, v250, v96
	v_cvt_pk_bf16_f32 v96, v96, v17
	v_add_f32_e32 v251, v41, v153
	v_lshlrev_b32_e32 v97, 16, v97
	v_mul_f32_e32 v97, v251, v97
	v_cvt_pk_bf16_f32 v97, v97, v17
	s_waitcnt vmcnt(63)
	v_add_f32_e32 v250, v26, v154
	v_lshlrev_b32_e32 v98, 16, v98
	v_mul_f32_e32 v98, v250, v98
	v_cvt_pk_bf16_f32 v98, v98, v17
	v_add_f32_e32 v251, v42, v154
	v_lshlrev_b32_e32 v99, 16, v99
	v_mul_f32_e32 v99, v251, v99
	v_cvt_pk_bf16_f32 v99, v99, v17
	s_waitcnt vmcnt(63)
	v_add_f32_e32 v250, v27, v155
	v_lshlrev_b32_e32 v100, 16, v100
	v_mul_f32_e32 v100, v250, v100
	v_cvt_pk_bf16_f32 v100, v100, v17
	v_add_f32_e32 v251, v43, v155
	v_lshlrev_b32_e32 v101, 16, v101
	v_mul_f32_e32 v101, v251, v101
	v_cvt_pk_bf16_f32 v101, v101, v17
	s_waitcnt vmcnt(63)
	v_add_f32_e32 v250, v28, v156
	v_lshlrev_b32_e32 v102, 16, v102
	v_mul_f32_e32 v102, v250, v102
	v_cvt_pk_bf16_f32 v102, v102, v17
	v_add_f32_e32 v251, v44, v156
	v_lshlrev_b32_e32 v103, 16, v103
	v_mul_f32_e32 v103, v251, v103
	v_cvt_pk_bf16_f32 v103, v103, v17
	s_waitcnt vmcnt(60)
	v_add_f32_e32 v250, v29, v157
	v_lshlrev_b32_e32 v104, 16, v104
	v_mul_f32_e32 v104, v250, v104
	v_cvt_pk_bf16_f32 v104, v104, v17
	v_add_f32_e32 v251, v45, v157
	v_lshlrev_b32_e32 v105, 16, v105
	v_mul_f32_e32 v105, v251, v105
	v_cvt_pk_bf16_f32 v105, v105, v17
	s_waitcnt vmcnt(57)
	v_add_f32_e32 v250, v30, v158
	v_lshlrev_b32_e32 v106, 16, v106
	v_mul_f32_e32 v106, v250, v106
	v_cvt_pk_bf16_f32 v106, v106, v17
	v_add_f32_e32 v251, v46, v158
	v_lshlrev_b32_e32 v107, 16, v107
	v_mul_f32_e32 v107, v251, v107
	v_cvt_pk_bf16_f32 v107, v107, v17
	s_waitcnt vmcnt(54)
	v_add_f32_e32 v250, v31, v159
	v_lshlrev_b32_e32 v108, 16, v108
	v_mul_f32_e32 v108, v250, v108
	v_cvt_pk_bf16_f32 v108, v108, v17
	v_add_f32_e32 v251, v47, v159
	v_lshlrev_b32_e32 v109, 16, v109
	v_mul_f32_e32 v109, v251, v109
	v_cvt_pk_bf16_f32 v109, v109, v17
	s_waitcnt vmcnt(51)
	v_add_f32_e32 v250, v32, v160
	v_lshlrev_b32_e32 v110, 16, v110
	v_mul_f32_e32 v110, v250, v110
	v_cvt_pk_bf16_f32 v110, v110, v17
	v_add_f32_e32 v251, v48, v160
	v_lshlrev_b32_e32 v111, 16, v111
	v_mul_f32_e32 v111, v251, v111
	v_cvt_pk_bf16_f32 v111, v111, v17
	s_waitcnt vmcnt(48)
	v_add_f32_e32 v250, v33, v161
	v_lshlrev_b32_e32 v112, 16, v112
	v_mul_f32_e32 v112, v250, v112
	v_cvt_pk_bf16_f32 v112, v112, v17
	v_add_f32_e32 v251, v49, v161
	v_lshlrev_b32_e32 v113, 16, v113
	v_mul_f32_e32 v113, v251, v113
	v_cvt_pk_bf16_f32 v113, v113, v17
	s_waitcnt vmcnt(45)
	v_add_f32_e32 v250, v50, v234
	v_lshlrev_b32_e32 v114, 16, v114
	v_mul_f32_e32 v114, v250, v114
	v_cvt_pk_bf16_f32 v114, v114, v17
	v_add_f32_e32 v251, v66, v234
	v_lshlrev_b32_e32 v115, 16, v115
	v_mul_f32_e32 v115, v251, v115
	v_cvt_pk_bf16_f32 v115, v115, v17
	s_waitcnt vmcnt(42)
	v_add_f32_e32 v250, v51, v235
	v_lshlrev_b32_e32 v116, 16, v116
	v_mul_f32_e32 v116, v250, v116
	v_cvt_pk_bf16_f32 v116, v116, v17
	v_add_f32_e32 v251, v67, v235
	v_lshlrev_b32_e32 v117, 16, v117
	v_mul_f32_e32 v117, v251, v117
	v_cvt_pk_bf16_f32 v117, v117, v17
	s_waitcnt vmcnt(39)
	v_add_f32_e32 v250, v52, v236
	v_lshlrev_b32_e32 v118, 16, v118
	v_mul_f32_e32 v118, v250, v118
	v_cvt_pk_bf16_f32 v118, v118, v17
	v_add_f32_e32 v251, v68, v236
	v_lshlrev_b32_e32 v119, 16, v119
	v_mul_f32_e32 v119, v251, v119
	v_cvt_pk_bf16_f32 v119, v119, v17
	s_waitcnt vmcnt(36)
	v_add_f32_e32 v250, v53, v237
	v_lshlrev_b32_e32 v120, 16, v120
	v_mul_f32_e32 v120, v250, v120
	v_cvt_pk_bf16_f32 v120, v120, v17
	v_add_f32_e32 v251, v69, v237
	v_lshlrev_b32_e32 v121, 16, v121
	v_mul_f32_e32 v121, v251, v121
	v_cvt_pk_bf16_f32 v121, v121, v17
	s_waitcnt vmcnt(33)
; __device__ __forceinline__ unsigned short bf1(float a) { return (unsigned short)(cvtpk(a, 0.f) & 0xffffu); }
; __device__ __forceinline__ int crow(int r, int hi) { return (r & 3) + 8 * (r >> 2) + 4 * hi; }
; __device__ __forceinline__ void gmlp_item(PARAMS_T& p, int l, int b, int pos0, int tokrow0) {
;     ...
; #pragma unroll
;   for (int tb = 0; tb < 2; ++tb)
; #pragma unroll
;     for (int r = 0; r < 16; ++r) {
;       const int t = th * 64 + tb * 32 + crow(r, hi);
;       const float bt = bs[t];
; #pragma unroll
;       for (int db = 0; db < 2; ++db) {
;         const int d = g * 64 + db * 32 + r32;
;         const float uv = __uint_as_float(((unsigned)u[(size_t)(tokrow0 + t) * 256 + d]) << 16);
;         outp[(size_t)(tokrow0 + t) * 1024 + 256 + d] = bf1(uv * (acc[tb][db][r] + bt));
;       }
	v_add_f32_e32 v250, v54, v238
	v_lshlrev_b32_e32 v122, 16, v122
	v_mul_f32_e32 v122, v250, v122
	v_cvt_pk_bf16_f32 v122, v122, v17
	v_add_f32_e32 v251, v70, v238
	v_lshlrev_b32_e32 v123, 16, v123
	v_mul_f32_e32 v123, v251, v123
	v_cvt_pk_bf16_f32 v123, v123, v17
	s_waitcnt vmcnt(30)
	v_add_f32_e32 v250, v55, v239
	v_lshlrev_b32_e32 v124, 16, v124
	v_mul_f32_e32 v124, v250, v124
	v_cvt_pk_bf16_f32 v124, v124, v17
	v_add_f32_e32 v251, v71, v239
	v_lshlrev_b32_e32 v125, 16, v125
	v_mul_f32_e32 v125, v251, v125
	v_cvt_pk_bf16_f32 v125, v125, v17
	s_waitcnt vmcnt(27)
	v_add_f32_e32 v250, v56, v240
	v_lshlrev_b32_e32 v126, 16, v126
	v_mul_f32_e32 v126, v250, v126
	v_cvt_pk_bf16_f32 v126, v126, v17
	v_add_f32_e32 v251, v72, v240
	v_lshlrev_b32_e32 v127, 16, v127
	v_mul_f32_e32 v127, v251, v127
	v_cvt_pk_bf16_f32 v127, v127, v17
	s_waitcnt vmcnt(24)
	v_add_f32_e32 v250, v57, v241
	v_lshlrev_b32_e32 v128, 16, v128
	v_mul_f32_e32 v128, v250, v128
	v_cvt_pk_bf16_f32 v128, v128, v17
	v_add_f32_e32 v251, v73, v241
	v_lshlrev_b32_e32 v129, 16, v129
	v_mul_f32_e32 v129, v251, v129
	v_cvt_pk_bf16_f32 v129, v129, v17
	s_waitcnt vmcnt(21)
	v_add_f32_e32 v250, v58, v242
	v_lshlrev_b32_e32 v130, 16, v130
	v_mul_f32_e32 v130, v250, v130
	v_cvt_pk_bf16_f32 v130, v130, v17
	v_add_f32_e32 v251, v74, v242
	v_lshlrev_b32_e32 v131, 16, v131
	v_mul_f32_e32 v131, v251, v131
	v_cvt_pk_bf16_f32 v131, v131, v17
	s_waitcnt vmcnt(18)
	v_add_f32_e32 v250, v59, v243
	v_lshlrev_b32_e32 v132, 16, v132
	v_mul_f32_e32 v132, v250, v132
	v_cvt_pk_bf16_f32 v132, v132, v17
	v_add_f32_e32 v251, v75, v243
	v_lshlrev_b32_e32 v133, 16, v133
	v_mul_f32_e32 v133, v251, v133
	v_cvt_pk_bf16_f32 v133, v133, v17
	s_waitcnt vmcnt(15)
	v_add_f32_e32 v250, v60, v244
	v_lshlrev_b32_e32 v134, 16, v134
	v_mul_f32_e32 v134, v250, v134
	v_cvt_pk_bf16_f32 v134, v134, v17
	v_add_f32_e32 v251, v76, v244
	v_lshlrev_b32_e32 v135, 16, v135
	v_mul_f32_e32 v135, v251, v135
	v_cvt_pk_bf16_f32 v135, v135, v17
	s_waitcnt vmcnt(12)
	v_add_f32_e32 v250, v61, v245
	v_lshlrev_b32_e32 v136, 16, v136
	v_mul_f32_e32 v136, v250, v136
	v_cvt_pk_bf16_f32 v136, v136, v17
	v_add_f32_e32 v251, v77, v245
	v_lshlrev_b32_e32 v137, 16, v137
	v_mul_f32_e32 v137, v251, v137
	v_cvt_pk_bf16_f32 v137, v137, v17
	s_waitcnt vmcnt(9)
	v_add_f32_e32 v250, v62, v246
	v_lshlrev_b32_e32 v138, 16, v138
	v_mul_f32_e32 v138, v250, v138
	v_cvt_pk_bf16_f32 v138, v138, v17
	v_add_f32_e32 v251, v78, v246
	v_lshlrev_b32_e32 v139, 16, v139
	v_mul_f32_e32 v139, v251, v139
	v_cvt_pk_bf16_f32 v139, v139, v17
	s_waitcnt vmcnt(6)
	v_add_f32_e32 v250, v63, v247
	v_lshlrev_b32_e32 v140, 16, v140
	v_mul_f32_e32 v140, v250, v140
	v_cvt_pk_bf16_f32 v140, v140, v17
	v_add_f32_e32 v251, v79, v247
	v_lshlrev_b32_e32 v141, 16, v141
	v_mul_f32_e32 v141, v251, v141
	v_cvt_pk_bf16_f32 v141, v141, v17
	s_waitcnt vmcnt(3)
	v_add_f32_e32 v250, v64, v248
	v_lshlrev_b32_e32 v142, 16, v142
	v_mul_f32_e32 v142, v250, v142
	v_cvt_pk_bf16_f32 v142, v142, v17
	v_add_f32_e32 v251, v80, v248
	v_lshlrev_b32_e32 v143, 16, v143
	v_mul_f32_e32 v143, v251, v143
	v_cvt_pk_bf16_f32 v143, v143, v17
	s_waitcnt vmcnt(0)
; __device__ __forceinline__ unsigned short bf1(float a) { return (unsigned short)(cvtpk(a, 0.f) & 0xffffu); }
; __device__ __forceinline__ int crow(int r, int hi) { return (r & 3) + 8 * (r >> 2) + 4 * hi; }
; __device__ __forceinline__ void gmlp_item(PARAMS_T& p, int l, int b, int pos0, int tokrow0) {
;     ...
; #pragma unroll
;   for (int tb = 0; tb < 2; ++tb)
; #pragma unroll
;     for (int r = 0; r < 16; ++r) {
;       const int t = th * 64 + tb * 32 + crow(r, hi);
;       const float bt = bs[t];
; #pragma unroll
;       for (int db = 0; db < 2; ++db) {
;         const int d = g * 64 + db * 32 + r32;
;         const float uv = __uint_as_float(((unsigned)u[(size_t)(tokrow0 + t) * 256 + d]) << 16);
;         outp[(size_t)(tokrow0 + t) * 1024 + 256 + d] = bf1(uv * (acc[tb][db][r] + bt));
;       }
;     }
	v_add_f32_e32 v250, v65, v249
	v_lshlrev_b32_e32 v144, 16, v144
	v_mul_f32_e32 v144, v250, v144
	v_cvt_pk_bf16_f32 v144, v144, v17
	v_add_f32_e32 v251, v81, v249
	v_lshlrev_b32_e32 v145, 16, v145
	v_mul_f32_e32 v145, v251, v145
	v_cvt_pk_bf16_f32 v145, v145, v17
	v_add_u32_e32 v254, 0, v171
	v_lshl_add_u32 v146, v254, 11, v172
	v_add_u32_e32 v254, 2, v171
	v_lshl_add_u32 v147, v254, 11, v172
	v_add_u32_e32 v254, 8, v171
	v_lshl_add_u32 v148, v254, 11, v172
	v_add_u32_e32 v254, 10, v171
	v_lshl_add_u32 v149, v254, 11, v172
	v_add_u32_e32 v254, 16, v171
	v_lshl_add_u32 v150, v254, 11, v172
	v_add_u32_e32 v254, 18, v171
	v_lshl_add_u32 v151, v254, 11, v172
	v_add_u32_e32 v254, 24, v171
	v_lshl_add_u32 v152, v254, 11, v172
	v_add_u32_e32 v254, 26, v171
	v_lshl_add_u32 v153, v254, 11, v172
	v_add_u32_e32 v254, 32, v171
	v_lshl_add_u32 v154, v254, 11, v172
	v_add_u32_e32 v254, 34, v171
	v_lshl_add_u32 v155, v254, 11, v172
	v_add_u32_e32 v254, 40, v171
	v_lshl_add_u32 v156, v254, 11, v172
	v_add_u32_e32 v254, 42, v171
	v_lshl_add_u32 v157, v254, 11, v172
	v_add_u32_e32 v254, 48, v171
	v_lshl_add_u32 v158, v254, 11, v172
	v_add_u32_e32 v254, 50, v171
	v_lshl_add_u32 v159, v254, 11, v172
	v_add_u32_e32 v254, 56, v171
	v_lshl_add_u32 v160, v254, 11, v172
	v_add_u32_e32 v254, 58, v171
	v_lshl_add_u32 v161, v254, 11, v172
	global_store_short v146, v82, s[96:97]
	global_store_short v146, v83, s[96:97] offset:64
	global_store_short v146, v84, s[96:97] offset:2048
	global_store_short v146, v85, s[96:97] offset:2112
	global_store_short v147, v86, s[96:97]
	global_store_short v147, v87, s[96:97] offset:64
	global_store_short v147, v88, s[96:97] offset:2048
	global_store_short v147, v89, s[96:97] offset:2112
	global_store_short v148, v90, s[96:97]
	global_store_short v148, v91, s[96:97] offset:64
	global_store_short v148, v92, s[96:97] offset:2048
	global_store_short v148, v93, s[96:97] offset:2112
	global_store_short v149, v94, s[96:97]
	global_store_short v149, v95, s[96:97] offset:64
	global_store_short v149, v96, s[96:97] offset:2048
	global_store_short v149, v97, s[96:97] offset:2112
	global_store_short v150, v98, s[96:97]
	global_store_short v150, v99, s[96:97] offset:64
	global_store_short v150, v100, s[96:97] offset:2048
	global_store_short v150, v101, s[96:97] offset:2112
	global_store_short v151, v102, s[96:97]
	global_store_short v151, v103, s[96:97] offset:64
	global_store_short v151, v104, s[96:97] offset:2048
	global_store_short v151, v105, s[96:97] offset:2112
	global_store_short v152, v106, s[96:97]
	global_store_short v152, v107, s[96:97] offset:64
	global_store_short v152, v108, s[96:97] offset:2048
	global_store_short v152, v109, s[96:97] offset:2112
	global_store_short v153, v110, s[96:97]
	global_store_short v153, v111, s[96:97] offset:64
	global_store_short v153, v112, s[96:97] offset:2048
	global_store_short v153, v113, s[96:97] offset:2112
	global_store_short v154, v114, s[96:97]
	global_store_short v154, v115, s[96:97] offset:64
	global_store_short v154, v116, s[96:97] offset:2048
	global_store_short v154, v117, s[96:97] offset:2112
	global_store_short v155, v118, s[96:97]
	global_store_short v155, v119, s[96:97] offset:64
	global_store_short v155, v120, s[96:97] offset:2048
	global_store_short v155, v121, s[96:97] offset:2112
	global_store_short v156, v122, s[96:97]
	global_store_short v156, v123, s[96:97] offset:64
	global_store_short v156, v124, s[96:97] offset:2048
	global_store_short v156, v125, s[96:97] offset:2112
	global_store_short v157, v126, s[96:97]
	global_store_short v157, v127, s[96:97] offset:64
	global_store_short v157, v128, s[96:97] offset:2048
	global_store_short v157, v129, s[96:97] offset:2112
	global_store_short v158, v130, s[96:97]
	global_store_short v158, v131, s[96:97] offset:64
	global_store_short v158, v132, s[96:97] offset:2048
	global_store_short v158, v133, s[96:97] offset:2112
	global_store_short v159, v134, s[96:97]
	global_store_short v159, v135, s[96:97] offset:64
	global_store_short v159, v136, s[96:97] offset:2048
	global_store_short v159, v137, s[96:97] offset:2112
	global_store_short v160, v138, s[96:97]
	global_store_short v160, v139, s[96:97] offset:64
	global_store_short v160, v140, s[96:97] offset:2048
	global_store_short v160, v141, s[96:97] offset:2112
	global_store_short v161, v142, s[96:97]
	global_store_short v161, v143, s[96:97] offset:64
	global_store_short v161, v144, s[96:97] offset:2048
	global_store_short v161, v145, s[96:97] offset:2112
	s_mov_b64 s[6:7], 0
